# stack34 + GEMM load segments: LDS fragment reads issued first after the barrier, LDS-DMA address arithmetic and issue after them (temps renamed)
# baseline (speedup 1.0000x reference)
.Lgprio0:
.LBB0_159:
	ds_read_b128 v[150:153], v147
	ds_read_b128 v[154:157], v147 offset:1024
	ds_read_b128 v[158:161], v147 offset:2048
	ds_read_b128 v[162:165], v147 offset:3072
	ds_read_b128 v[166:169], v148
	ds_read_b128 v[170:173], v148 offset:1024
	ds_read_b128 v[174:177], v148 offset:2048
	ds_read_b128 v[178:181], v148 offset:3072
	ds_read_b128 v[182:185], v149
	ds_read_b128 v[186:189], v149 offset:1024
	ds_read_b128 v[190:193], v149 offset:2048
	ds_read_b128 v[194:197], v149 offset:3072
	ds_read_b128 v[198:201], v149 offset:4096
	ds_read_b128 v[202:205], v149 offset:5120
	ds_read_b128 v[206:209], v149 offset:6144
	ds_read_b128 v[210:213], v149 offset:7168
	s_add_u32 s38, s36, 0x100
	s_addc_u32 s39, s37, 0
	s_cmp_eq_u32 s59, 28
	s_cselect_b32 s43, s19, s39
	s_cselect_b32 s42, s55, s38
	s_cselect_b32 s41, s17, s58
	s_cselect_b32 s40, s56, s57
	v_lshl_add_u64 v[228:229], s[36:37], 0, v[136:137]
	s_add_i32 m0, s35, 0xc000
	s_nop 0
	global_load_lds_dwordx4 v[228:229], off
	v_lshl_add_u64 v[228:229], s[36:37], 0, v[138:139]
	s_add_i32 m0, s35, 0xe000
	s_nop 0
	global_load_lds_dwordx4 v[228:229], off
	s_waitcnt vmcnt(8)
	s_waitcnt lgkmcnt(0)
	s_barrier
	s_waitcnt lgkmcnt(0)
	v_mfma_f32_16x16x32_bf16 v[124:127], v[150:153], v[182:185], v[124:127]
	v_mfma_f32_16x16x32_bf16 v[120:123], v[158:161], v[182:185], v[120:123]
	v_mfma_f32_16x16x32_bf16 v[108:111], v[150:153], v[190:193], v[108:111]
	v_mfma_f32_16x16x32_bf16 v[104:107], v[158:161], v[190:193], v[104:107]
	v_mfma_f32_16x16x32_bf16 v[92:95], v[150:153], v[198:201], v[92:95]
	v_mfma_f32_16x16x32_bf16 v[88:91], v[158:161], v[198:201], v[88:91]
	v_mfma_f32_16x16x32_bf16 v[76:79], v[150:153], v[206:209], v[76:79]
	v_mfma_f32_16x16x32_bf16 v[72:75], v[158:161], v[206:209], v[72:75]
	v_mfma_f32_16x16x32_bf16 v[124:127], v[154:157], v[186:189], v[124:127]
	v_mfma_f32_16x16x32_bf16 v[120:123], v[162:165], v[186:189], v[120:123]
	v_mfma_f32_16x16x32_bf16 v[108:111], v[154:157], v[194:197], v[108:111]
	v_mfma_f32_16x16x32_bf16 v[104:107], v[162:165], v[194:197], v[104:107]
	v_mfma_f32_16x16x32_bf16 v[92:95], v[154:157], v[202:205], v[92:95]
	v_mfma_f32_16x16x32_bf16 v[88:91], v[162:165], v[202:205], v[88:91]
	v_mfma_f32_16x16x32_bf16 v[76:79], v[154:157], v[210:213], v[76:79]
	v_mfma_f32_16x16x32_bf16 v[72:75], v[162:165], v[210:213], v[72:75]
	v_mfma_f32_16x16x32_bf16 v[116:119], v[166:169], v[182:185], v[116:119]
	v_mfma_f32_16x16x32_bf16 v[112:115], v[174:177], v[182:185], v[112:115]
	v_mfma_f32_16x16x32_bf16 v[100:103], v[166:169], v[190:193], v[100:103]
	v_mfma_f32_16x16x32_bf16 v[96:99], v[174:177], v[190:193], v[96:99]
	v_mfma_f32_16x16x32_bf16 v[84:87], v[166:169], v[198:201], v[84:87]
	v_mfma_f32_16x16x32_bf16 v[80:83], v[174:177], v[198:201], v[80:83]
	v_mfma_f32_16x16x32_bf16 v[68:71], v[166:169], v[206:209], v[68:71]
	v_mfma_f32_16x16x32_bf16 v[64:67], v[174:177], v[206:209], v[64:67]
	v_mfma_f32_16x16x32_bf16 v[116:119], v[170:173], v[186:189], v[116:119]
	v_mfma_f32_16x16x32_bf16 v[112:115], v[178:181], v[186:189], v[112:115]
	v_mfma_f32_16x16x32_bf16 v[100:103], v[170:173], v[194:197], v[100:103]
	v_mfma_f32_16x16x32_bf16 v[96:99], v[178:181], v[194:197], v[96:99]
	v_mfma_f32_16x16x32_bf16 v[84:87], v[170:173], v[202:205], v[84:87]
	v_mfma_f32_16x16x32_bf16 v[80:83], v[178:181], v[202:205], v[80:83]
	v_mfma_f32_16x16x32_bf16 v[68:71], v[170:173], v[210:213], v[68:71]
	v_mfma_f32_16x16x32_bf16 v[64:67], v[178:181], v[210:213], v[64:67]
	s_barrier
	ds_read_b128 v[182:185], v149 offset:16384
	ds_read_b128 v[186:189], v149 offset:17408
	ds_read_b128 v[190:193], v149 offset:18432
	ds_read_b128 v[194:197], v149 offset:19456
	ds_read_b128 v[198:201], v149 offset:20480
	ds_read_b128 v[202:205], v149 offset:21504
	ds_read_b128 v[206:209], v149 offset:22528
	ds_read_b128 v[210:213], v149 offset:23552
	s_add_i32 s36, s51, s11
	v_lshl_add_u64 v[214:215], s[40:41], 0, v[130:131]
	s_mov_b32 m0, s36
	v_lshl_add_u64 v[216:217], s[40:41], 0, v[134:135]
	global_load_lds_dwordx4 v[214:215], off
	s_add_i32 m0, s36, 0x2000
	s_add_u32 s36, s40, 0x80000
	s_addc_u32 s37, s41, 0
	s_add_i32 s60, s52, s11
	global_load_lds_dwordx4 v[216:217], off
	v_lshl_add_u64 v[228:229], s[36:37], 0, v[130:131]
	s_mov_b32 m0, s60
	v_lshl_add_u64 v[218:219], s[42:43], 0, v[128:129]
	global_load_lds_dwordx4 v[228:229], off
	v_lshl_add_u64 v[228:229], s[36:37], 0, v[134:135]
	s_add_i32 m0, s60, 0x2000
	v_lshl_add_u64 v[220:221], s[42:43], 0, v[132:133]
	global_load_lds_dwordx4 v[228:229], off
	s_mov_b32 m0, s35
	s_nop 0
	global_load_lds_dwordx4 v[218:219], off
	s_mov_b32 m0, s44
	s_nop 0
	global_load_lds_dwordx4 v[220:221], off
	s_waitcnt vmcnt(8)
	s_waitcnt lgkmcnt(0)
	s_barrier
	s_waitcnt lgkmcnt(0)
	v_mfma_f32_16x16x32_bf16 v[60:63], v[150:153], v[182:185], v[60:63]
	v_mfma_f32_16x16x32_bf16 v[56:59], v[158:161], v[182:185], v[56:59]
	v_mfma_f32_16x16x32_bf16 v[44:47], v[150:153], v[190:193], v[44:47]
	v_mfma_f32_16x16x32_bf16 v[40:43], v[158:161], v[190:193], v[40:43]
	v_mfma_f32_16x16x32_bf16 v[28:31], v[150:153], v[198:201], v[28:31]
	v_mfma_f32_16x16x32_bf16 v[24:27], v[158:161], v[198:201], v[24:27]
	v_mfma_f32_16x16x32_bf16 v[12:15], v[150:153], v[206:209], v[12:15]
	v_mfma_f32_16x16x32_bf16 v[8:11], v[158:161], v[206:209], v[8:11]
	v_mfma_f32_16x16x32_bf16 v[60:63], v[154:157], v[186:189], v[60:63]
	v_mfma_f32_16x16x32_bf16 v[56:59], v[162:165], v[186:189], v[56:59]
	v_mfma_f32_16x16x32_bf16 v[44:47], v[154:157], v[194:197], v[44:47]
	v_mfma_f32_16x16x32_bf16 v[40:43], v[162:165], v[194:197], v[40:43]
	v_mfma_f32_16x16x32_bf16 v[28:31], v[154:157], v[202:205], v[28:31]
	v_mfma_f32_16x16x32_bf16 v[24:27], v[162:165], v[202:205], v[24:27]
	v_mfma_f32_16x16x32_bf16 v[12:15], v[154:157], v[210:213], v[12:15]
	v_mfma_f32_16x16x32_bf16 v[8:11], v[162:165], v[210:213], v[8:11]
	v_mfma_f32_16x16x32_bf16 v[52:55], v[166:169], v[182:185], v[52:55]
	v_mfma_f32_16x16x32_bf16 v[48:51], v[174:177], v[182:185], v[48:51]
	v_mfma_f32_16x16x32_bf16 v[36:39], v[166:169], v[190:193], v[36:39]
	v_mfma_f32_16x16x32_bf16 v[32:35], v[174:177], v[190:193], v[32:35]
	v_mfma_f32_16x16x32_bf16 v[20:23], v[166:169], v[198:201], v[20:23]
	v_mfma_f32_16x16x32_bf16 v[16:19], v[174:177], v[198:201], v[16:19]
	v_mfma_f32_16x16x32_bf16 v[4:7], v[166:169], v[206:209], v[4:7]
	v_mfma_f32_16x16x32_bf16 v[0:3], v[174:177], v[206:209], v[0:3]
	v_mfma_f32_16x16x32_bf16 v[52:55], v[170:173], v[186:189], v[52:55]
	v_mfma_f32_16x16x32_bf16 v[48:51], v[178:181], v[186:189], v[48:51]
	v_mfma_f32_16x16x32_bf16 v[36:39], v[170:173], v[194:197], v[36:39]
	v_mfma_f32_16x16x32_bf16 v[32:35], v[178:181], v[194:197], v[32:35]
	v_mfma_f32_16x16x32_bf16 v[20:23], v[170:173], v[202:205], v[20:23]
	v_mfma_f32_16x16x32_bf16 v[16:19], v[178:181], v[202:205], v[16:19]
	v_mfma_f32_16x16x32_bf16 v[4:7], v[170:173], v[210:213], v[4:7]
	v_mfma_f32_16x16x32_bf16 v[0:3], v[178:181], v[210:213], v[0:3]
	s_barrier
	s_add_i32 s60, 0, 0x18000
	s_add_i32 s61, 0, 0x1c000
	v_add_u32_e32 v162, s60, v144
	v_add_u32_e32 v178, s61, v144
	ds_read_b128 v[150:153], v162
	ds_read_b128 v[154:157], v162 offset:1024
	ds_read_b128 v[158:161], v162 offset:2048
	ds_read_b128 v[162:165], v162 offset:3072
	ds_read_b128 v[166:169], v178
	ds_read_b128 v[170:173], v178 offset:1024
	ds_read_b128 v[174:177], v178 offset:2048
	ds_read_b128 v[178:181], v178 offset:3072
	ds_read_b128 v[182:185], v149 offset:32768
	ds_read_b128 v[186:189], v149 offset:33792
	ds_read_b128 v[190:193], v149 offset:34816
	ds_read_b128 v[194:197], v149 offset:35840
	ds_read_b128 v[198:201], v149 offset:36864
	ds_read_b128 v[202:205], v149 offset:37888
	ds_read_b128 v[206:209], v149 offset:38912
	ds_read_b128 v[210:213], v149 offset:39936
	s_add_u32 s36, s42, 0x80000
	s_addc_u32 s37, s43, 0
	s_mov_b32 m0, s45
	v_lshl_add_u64 v[228:229], s[36:37], 0, v[128:129]
	global_load_lds_dwordx4 v[228:229], off
	v_lshl_add_u64 v[228:229], s[36:37], 0, v[132:133]
	s_mov_b32 m0, s46
	s_nop 0
	global_load_lds_dwordx4 v[228:229], off
	s_waitcnt vmcnt(8)
	s_waitcnt lgkmcnt(0)
	s_barrier
	s_waitcnt lgkmcnt(0)
	v_mfma_f32_16x16x32_bf16 v[124:127], v[150:153], v[182:185], v[124:127]
	v_mfma_f32_16x16x32_bf16 v[120:123], v[158:161], v[182:185], v[120:123]
	v_mfma_f32_16x16x32_bf16 v[108:111], v[150:153], v[190:193], v[108:111]
	v_mfma_f32_16x16x32_bf16 v[104:107], v[158:161], v[190:193], v[104:107]
	v_mfma_f32_16x16x32_bf16 v[92:95], v[150:153], v[198:201], v[92:95]
	v_mfma_f32_16x16x32_bf16 v[88:91], v[158:161], v[198:201], v[88:91]
	v_mfma_f32_16x16x32_bf16 v[76:79], v[150:153], v[206:209], v[76:79]
	v_mfma_f32_16x16x32_bf16 v[72:75], v[158:161], v[206:209], v[72:75]
	v_mfma_f32_16x16x32_bf16 v[124:127], v[154:157], v[186:189], v[124:127]
	v_mfma_f32_16x16x32_bf16 v[120:123], v[162:165], v[186:189], v[120:123]
	v_mfma_f32_16x16x32_bf16 v[108:111], v[154:157], v[194:197], v[108:111]
	v_mfma_f32_16x16x32_bf16 v[104:107], v[162:165], v[194:197], v[104:107]
	v_mfma_f32_16x16x32_bf16 v[92:95], v[154:157], v[202:205], v[92:95]
	v_mfma_f32_16x16x32_bf16 v[88:91], v[162:165], v[202:205], v[88:91]
	v_mfma_f32_16x16x32_bf16 v[76:79], v[154:157], v[210:213], v[76:79]
	v_mfma_f32_16x16x32_bf16 v[72:75], v[162:165], v[210:213], v[72:75]
	v_mfma_f32_16x16x32_bf16 v[116:119], v[166:169], v[182:185], v[116:119]
	v_mfma_f32_16x16x32_bf16 v[112:115], v[174:177], v[182:185], v[112:115]
	v_mfma_f32_16x16x32_bf16 v[100:103], v[166:169], v[190:193], v[100:103]
	v_mfma_f32_16x16x32_bf16 v[96:99], v[174:177], v[190:193], v[96:99]
	v_mfma_f32_16x16x32_bf16 v[84:87], v[166:169], v[198:201], v[84:87]
	v_mfma_f32_16x16x32_bf16 v[80:83], v[174:177], v[198:201], v[80:83]
	v_mfma_f32_16x16x32_bf16 v[68:71], v[166:169], v[206:209], v[68:71]
	v_mfma_f32_16x16x32_bf16 v[64:67], v[174:177], v[206:209], v[64:67]
	v_mfma_f32_16x16x32_bf16 v[116:119], v[170:173], v[186:189], v[116:119]
	v_mfma_f32_16x16x32_bf16 v[112:115], v[178:181], v[186:189], v[112:115]
	v_mfma_f32_16x16x32_bf16 v[100:103], v[170:173], v[194:197], v[100:103]
	v_mfma_f32_16x16x32_bf16 v[96:99], v[178:181], v[194:197], v[96:99]
	v_mfma_f32_16x16x32_bf16 v[84:87], v[170:173], v[202:205], v[84:87]
	v_mfma_f32_16x16x32_bf16 v[80:83], v[178:181], v[202:205], v[80:83]
	v_mfma_f32_16x16x32_bf16 v[68:71], v[170:173], v[210:213], v[68:71]
	v_mfma_f32_16x16x32_bf16 v[64:67], v[178:181], v[210:213], v[64:67]
	s_barrier
	ds_read_b128 v[182:185], v149 offset:49152
	ds_read_b128 v[186:189], v149 offset:50176
	ds_read_b128 v[190:193], v149 offset:51200
	ds_read_b128 v[194:197], v149 offset:52224
	ds_read_b128 v[198:201], v149 offset:53248
	ds_read_b128 v[202:205], v149 offset:54272
	ds_read_b128 v[206:209], v149 offset:55296
	ds_read_b128 v[210:213], v149 offset:56320
	s_add_i32 s36, s60, s11
	v_lshl_add_u64 v[228:229], v[214:215], 0, s[14:15]
	s_mov_b32 m0, s36
	s_nop 0
	global_load_lds_dwordx4 v[228:229], off
	s_add_i32 m0, s36, 0x2000
	s_add_u32 s36, s40, 0x80080
	v_lshl_add_u64 v[228:229], v[216:217], 0, s[14:15]
	s_addc_u32 s37, s41, 0
	s_add_i32 s40, s61, s11
	global_load_lds_dwordx4 v[228:229], off
	v_lshl_add_u64 v[228:229], s[36:37], 0, v[130:131]
	s_mov_b32 m0, s40
	s_nop 0
	global_load_lds_dwordx4 v[228:229], off
	v_lshl_add_u64 v[228:229], s[36:37], 0, v[134:135]
	s_add_i32 m0, s40, 0x2000
	s_nop 0
	global_load_lds_dwordx4 v[228:229], off
	v_lshl_add_u64 v[228:229], v[218:219], 0, s[14:15]
	s_mov_b32 m0, s49
	s_nop 0
	global_load_lds_dwordx4 v[228:229], off
	v_lshl_add_u64 v[228:229], v[220:221], 0, s[14:15]
	s_mov_b32 m0, s50
	s_nop 0
	global_load_lds_dwordx4 v[228:229], off
	s_waitcnt vmcnt(8)
	s_waitcnt lgkmcnt(0)
	s_barrier
	s_waitcnt lgkmcnt(0)
	v_mfma_f32_16x16x32_bf16 v[60:63], v[150:153], v[182:185], v[60:63]
	v_mfma_f32_16x16x32_bf16 v[56:59], v[158:161], v[182:185], v[56:59]
	v_mfma_f32_16x16x32_bf16 v[44:47], v[150:153], v[190:193], v[44:47]
	v_mfma_f32_16x16x32_bf16 v[40:43], v[158:161], v[190:193], v[40:43]
	v_mfma_f32_16x16x32_bf16 v[28:31], v[150:153], v[198:201], v[28:31]
	v_mfma_f32_16x16x32_bf16 v[24:27], v[158:161], v[198:201], v[24:27]
	v_mfma_f32_16x16x32_bf16 v[12:15], v[150:153], v[206:209], v[12:15]
	v_mfma_f32_16x16x32_bf16 v[8:11], v[158:161], v[206:209], v[8:11]
	v_mfma_f32_16x16x32_bf16 v[60:63], v[154:157], v[186:189], v[60:63]
	v_mfma_f32_16x16x32_bf16 v[56:59], v[162:165], v[186:189], v[56:59]
	v_mfma_f32_16x16x32_bf16 v[44:47], v[154:157], v[194:197], v[44:47]
	v_mfma_f32_16x16x32_bf16 v[40:43], v[162:165], v[194:197], v[40:43]
	v_mfma_f32_16x16x32_bf16 v[28:31], v[154:157], v[202:205], v[28:31]
	v_mfma_f32_16x16x32_bf16 v[24:27], v[162:165], v[202:205], v[24:27]
	v_mfma_f32_16x16x32_bf16 v[12:15], v[154:157], v[210:213], v[12:15]
	v_mfma_f32_16x16x32_bf16 v[8:11], v[162:165], v[210:213], v[8:11]
	v_mfma_f32_16x16x32_bf16 v[52:55], v[166:169], v[182:185], v[52:55]
	v_mfma_f32_16x16x32_bf16 v[48:51], v[174:177], v[182:185], v[48:51]
	v_mfma_f32_16x16x32_bf16 v[36:39], v[166:169], v[190:193], v[36:39]
	v_mfma_f32_16x16x32_bf16 v[32:35], v[174:177], v[190:193], v[32:35]
	v_mfma_f32_16x16x32_bf16 v[20:23], v[166:169], v[198:201], v[20:23]
	v_mfma_f32_16x16x32_bf16 v[16:19], v[174:177], v[198:201], v[16:19]
	v_mfma_f32_16x16x32_bf16 v[4:7], v[166:169], v[206:209], v[4:7]
	v_mfma_f32_16x16x32_bf16 v[0:3], v[174:177], v[206:209], v[0:3]
	v_mfma_f32_16x16x32_bf16 v[52:55], v[170:173], v[186:189], v[52:55]
	v_mfma_f32_16x16x32_bf16 v[48:51], v[178:181], v[186:189], v[48:51]
	v_mfma_f32_16x16x32_bf16 v[36:39], v[170:173], v[194:197], v[36:39]
	v_mfma_f32_16x16x32_bf16 v[32:35], v[178:181], v[194:197], v[32:35]
	v_mfma_f32_16x16x32_bf16 v[20:23], v[170:173], v[202:205], v[20:23]
	v_mfma_f32_16x16x32_bf16 v[16:19], v[178:181], v[202:205], v[16:19]
	v_mfma_f32_16x16x32_bf16 v[4:7], v[170:173], v[210:213], v[4:7]
	v_mfma_f32_16x16x32_bf16 v[0:3], v[178:181], v[210:213], v[0:3]
	s_barrier
	s_add_i32 s59, s59, 2
	s_add_u32 s57, s57, 0x100
	s_addc_u32 s58, s58, 0
	s_cmp_gt_u32 s59, 29
	s_mov_b64 s[36:37], s[38:39]
	s_cbranch_scc0 .LBB0_159
	s_setprio 0
	s_and_b64 vcc, exec, s[6:7]
	s_cbranch_vccz .LBB0_162
	s_barrier

.Lgprio1:
.LBB0_248:
	ds_read_b128 v[144:147], v161
	ds_read_b128 v[148:151], v161 offset:1024
	ds_read_b128 v[152:155], v161 offset:2048
	ds_read_b128 v[164:167], v161 offset:3072
	ds_read_b128 v[168:171], v162
	ds_read_b128 v[172:175], v162 offset:1024
	ds_read_b128 v[176:179], v162 offset:2048
	ds_read_b128 v[180:183], v162 offset:3072
	ds_read_b128 v[184:187], v163
	ds_read_b128 v[188:191], v163 offset:1024
	ds_read_b128 v[192:195], v163 offset:2048
	ds_read_b128 v[196:199], v163 offset:3072
	ds_read_b128 v[200:203], v163 offset:4096
	ds_read_b128 v[204:207], v163 offset:5120
	ds_read_b128 v[208:211], v163 offset:6144
	ds_read_b128 v[212:215], v163 offset:7168
	s_add_u32 s6, s8, 0x100
	s_addc_u32 s7, s9, 0
	s_cmpk_eq_i32 s65, 0x54
	s_cselect_b32 s49, s43, s7
	s_cselect_b32 s48, s42, s6
	s_cselect_b32 s47, s45, s64
	s_cselect_b32 s46, s44, s63
	v_lshl_add_u64 v[228:229], s[8:9], 0, v[136:137]
	s_add_i32 m0, s53, 0xc000
	s_nop 0
	global_load_lds_dwordx4 v[228:229], off
	v_lshl_add_u64 v[228:229], s[8:9], 0, v[138:139]
	s_add_i32 m0, s53, 0xe000
	s_nop 0
	global_load_lds_dwordx4 v[228:229], off
	s_waitcnt vmcnt(8)
	s_waitcnt lgkmcnt(0)
	s_barrier
	s_waitcnt lgkmcnt(0)
	v_mfma_f32_16x16x32_bf16 v[124:127], v[144:147], v[184:187], v[124:127]
	v_mfma_f32_16x16x32_bf16 v[120:123], v[152:155], v[184:187], v[120:123]
	v_mfma_f32_16x16x32_bf16 v[108:111], v[144:147], v[192:195], v[108:111]
	v_mfma_f32_16x16x32_bf16 v[104:107], v[152:155], v[192:195], v[104:107]
	v_mfma_f32_16x16x32_bf16 v[92:95], v[144:147], v[200:203], v[92:95]
	v_mfma_f32_16x16x32_bf16 v[88:91], v[152:155], v[200:203], v[88:91]
	v_mfma_f32_16x16x32_bf16 v[76:79], v[144:147], v[208:211], v[76:79]
	v_mfma_f32_16x16x32_bf16 v[72:75], v[152:155], v[208:211], v[72:75]
	v_mfma_f32_16x16x32_bf16 v[124:127], v[148:151], v[188:191], v[124:127]
	v_mfma_f32_16x16x32_bf16 v[120:123], v[164:167], v[188:191], v[120:123]
	v_mfma_f32_16x16x32_bf16 v[108:111], v[148:151], v[196:199], v[108:111]
	v_mfma_f32_16x16x32_bf16 v[104:107], v[164:167], v[196:199], v[104:107]
	v_mfma_f32_16x16x32_bf16 v[92:95], v[148:151], v[204:207], v[92:95]
	v_mfma_f32_16x16x32_bf16 v[88:91], v[164:167], v[204:207], v[88:91]
	v_mfma_f32_16x16x32_bf16 v[76:79], v[148:151], v[212:215], v[76:79]
	v_mfma_f32_16x16x32_bf16 v[72:75], v[164:167], v[212:215], v[72:75]
	v_mfma_f32_16x16x32_bf16 v[116:119], v[168:171], v[184:187], v[116:119]
	v_mfma_f32_16x16x32_bf16 v[112:115], v[176:179], v[184:187], v[112:115]
	v_mfma_f32_16x16x32_bf16 v[100:103], v[168:171], v[192:195], v[100:103]
	v_mfma_f32_16x16x32_bf16 v[96:99], v[176:179], v[192:195], v[96:99]
	v_mfma_f32_16x16x32_bf16 v[84:87], v[168:171], v[200:203], v[84:87]
	v_mfma_f32_16x16x32_bf16 v[80:83], v[176:179], v[200:203], v[80:83]
	v_mfma_f32_16x16x32_bf16 v[68:71], v[168:171], v[208:211], v[68:71]
	v_mfma_f32_16x16x32_bf16 v[64:67], v[176:179], v[208:211], v[64:67]
	v_mfma_f32_16x16x32_bf16 v[116:119], v[172:175], v[188:191], v[116:119]
	v_mfma_f32_16x16x32_bf16 v[112:115], v[180:183], v[188:191], v[112:115]
	v_mfma_f32_16x16x32_bf16 v[100:103], v[172:175], v[196:199], v[100:103]
	v_mfma_f32_16x16x32_bf16 v[96:99], v[180:183], v[196:199], v[96:99]
	v_mfma_f32_16x16x32_bf16 v[84:87], v[172:175], v[204:207], v[84:87]
	v_mfma_f32_16x16x32_bf16 v[80:83], v[180:183], v[204:207], v[80:83]
	v_mfma_f32_16x16x32_bf16 v[68:71], v[172:175], v[212:215], v[68:71]
	v_mfma_f32_16x16x32_bf16 v[64:67], v[180:183], v[212:215], v[64:67]
	s_barrier
	ds_read_b128 v[184:187], v163 offset:16384
	ds_read_b128 v[188:191], v163 offset:17408
	ds_read_b128 v[192:195], v163 offset:18432
	ds_read_b128 v[196:199], v163 offset:19456
	ds_read_b128 v[200:203], v163 offset:20480
	ds_read_b128 v[204:207], v163 offset:21504
	ds_read_b128 v[208:211], v163 offset:22528
	ds_read_b128 v[212:215], v163 offset:23552
	s_add_i32 s8, s58, s21
	v_lshl_add_u64 v[216:217], s[46:47], 0, v[130:131]
	s_mov_b32 m0, s8
	v_lshl_add_u64 v[218:219], s[46:47], 0, v[134:135]
	global_load_lds_dwordx4 v[216:217], off
	s_add_i32 m0, s8, 0x2000
	s_add_u32 s8, s46, 0x160000
	s_addc_u32 s9, s47, 0
	s_add_i32 s66, s59, s21
	global_load_lds_dwordx4 v[218:219], off
	v_lshl_add_u64 v[228:229], s[8:9], 0, v[130:131]
	s_mov_b32 m0, s66
	v_lshl_add_u64 v[220:221], s[48:49], 0, v[128:129]
	global_load_lds_dwordx4 v[228:229], off
	v_lshl_add_u64 v[228:229], s[8:9], 0, v[134:135]
	s_add_i32 m0, s66, 0x2000
	v_lshl_add_u64 v[222:223], s[48:49], 0, v[132:133]
	global_load_lds_dwordx4 v[228:229], off
	s_mov_b32 m0, s53
	s_nop 0
	global_load_lds_dwordx4 v[220:221], off
	s_mov_b32 m0, s54
	s_nop 0
	global_load_lds_dwordx4 v[222:223], off
	s_waitcnt vmcnt(8)
	s_waitcnt lgkmcnt(0)
	s_barrier
	s_waitcnt lgkmcnt(0)
	v_mfma_f32_16x16x32_bf16 v[60:63], v[144:147], v[184:187], v[60:63]
	v_mfma_f32_16x16x32_bf16 v[56:59], v[152:155], v[184:187], v[56:59]
	v_mfma_f32_16x16x32_bf16 v[44:47], v[144:147], v[192:195], v[44:47]
	v_mfma_f32_16x16x32_bf16 v[40:43], v[152:155], v[192:195], v[40:43]
	v_mfma_f32_16x16x32_bf16 v[28:31], v[144:147], v[200:203], v[28:31]
	v_mfma_f32_16x16x32_bf16 v[24:27], v[152:155], v[200:203], v[24:27]
	v_mfma_f32_16x16x32_bf16 v[12:15], v[144:147], v[208:211], v[12:15]
	v_mfma_f32_16x16x32_bf16 v[8:11], v[152:155], v[208:211], v[8:11]
	v_mfma_f32_16x16x32_bf16 v[60:63], v[148:151], v[188:191], v[60:63]
	v_mfma_f32_16x16x32_bf16 v[56:59], v[164:167], v[188:191], v[56:59]
	v_mfma_f32_16x16x32_bf16 v[44:47], v[148:151], v[196:199], v[44:47]
	v_mfma_f32_16x16x32_bf16 v[40:43], v[164:167], v[196:199], v[40:43]
	v_mfma_f32_16x16x32_bf16 v[28:31], v[148:151], v[204:207], v[28:31]
	v_mfma_f32_16x16x32_bf16 v[24:27], v[164:167], v[204:207], v[24:27]
	v_mfma_f32_16x16x32_bf16 v[12:15], v[148:151], v[212:215], v[12:15]
	v_mfma_f32_16x16x32_bf16 v[8:11], v[164:167], v[212:215], v[8:11]
	v_mfma_f32_16x16x32_bf16 v[52:55], v[168:171], v[184:187], v[52:55]
	v_mfma_f32_16x16x32_bf16 v[48:51], v[176:179], v[184:187], v[48:51]
	v_mfma_f32_16x16x32_bf16 v[36:39], v[168:171], v[192:195], v[36:39]
	v_mfma_f32_16x16x32_bf16 v[32:35], v[176:179], v[192:195], v[32:35]
	v_mfma_f32_16x16x32_bf16 v[20:23], v[168:171], v[200:203], v[20:23]
	v_mfma_f32_16x16x32_bf16 v[16:19], v[176:179], v[200:203], v[16:19]
	v_mfma_f32_16x16x32_bf16 v[4:7], v[168:171], v[208:211], v[4:7]
	v_mfma_f32_16x16x32_bf16 v[0:3], v[176:179], v[208:211], v[0:3]
	v_mfma_f32_16x16x32_bf16 v[52:55], v[172:175], v[188:191], v[52:55]
	v_mfma_f32_16x16x32_bf16 v[48:51], v[180:183], v[188:191], v[48:51]
	v_mfma_f32_16x16x32_bf16 v[36:39], v[172:175], v[196:199], v[36:39]
	v_mfma_f32_16x16x32_bf16 v[32:35], v[180:183], v[196:199], v[32:35]
	v_mfma_f32_16x16x32_bf16 v[20:23], v[172:175], v[204:207], v[20:23]
	v_mfma_f32_16x16x32_bf16 v[16:19], v[180:183], v[204:207], v[16:19]
	v_mfma_f32_16x16x32_bf16 v[4:7], v[172:175], v[212:215], v[4:7]
	v_mfma_f32_16x16x32_bf16 v[0:3], v[180:183], v[212:215], v[0:3]
	s_barrier
	s_add_i32 s66, 0, 0x18000
	s_add_i32 s67, 0, 0x1c000
	v_add_u32_e32 v164, s66, v156
	v_add_u32_e32 v180, s67, v156
	ds_read_b128 v[144:147], v164
	ds_read_b128 v[148:151], v164 offset:1024
	ds_read_b128 v[152:155], v164 offset:2048
	ds_read_b128 v[164:167], v164 offset:3072
	ds_read_b128 v[168:171], v180
	ds_read_b128 v[172:175], v180 offset:1024
	ds_read_b128 v[176:179], v180 offset:2048
	ds_read_b128 v[180:183], v180 offset:3072
	ds_read_b128 v[184:187], v163 offset:32768
	ds_read_b128 v[188:191], v163 offset:33792
	ds_read_b128 v[192:195], v163 offset:34816
	ds_read_b128 v[196:199], v163 offset:35840
	ds_read_b128 v[200:203], v163 offset:36864
	ds_read_b128 v[204:207], v163 offset:37888
	ds_read_b128 v[208:211], v163 offset:38912
	ds_read_b128 v[212:215], v163 offset:39936
	s_add_u32 s8, s48, 0x160000
	s_addc_u32 s9, s49, 0
	s_mov_b32 m0, s55
	v_lshl_add_u64 v[228:229], s[8:9], 0, v[128:129]
	global_load_lds_dwordx4 v[228:229], off
	v_lshl_add_u64 v[228:229], s[8:9], 0, v[132:133]
	s_mov_b32 m0, s56
	s_nop 0
	global_load_lds_dwordx4 v[228:229], off
	s_waitcnt vmcnt(8)
	s_waitcnt lgkmcnt(0)
	s_barrier
	s_waitcnt lgkmcnt(0)
	v_mfma_f32_16x16x32_bf16 v[124:127], v[144:147], v[184:187], v[124:127]
	v_mfma_f32_16x16x32_bf16 v[120:123], v[152:155], v[184:187], v[120:123]
	v_mfma_f32_16x16x32_bf16 v[108:111], v[144:147], v[192:195], v[108:111]
	v_mfma_f32_16x16x32_bf16 v[104:107], v[152:155], v[192:195], v[104:107]
	v_mfma_f32_16x16x32_bf16 v[92:95], v[144:147], v[200:203], v[92:95]
	v_mfma_f32_16x16x32_bf16 v[88:91], v[152:155], v[200:203], v[88:91]
	v_mfma_f32_16x16x32_bf16 v[76:79], v[144:147], v[208:211], v[76:79]
	v_mfma_f32_16x16x32_bf16 v[72:75], v[152:155], v[208:211], v[72:75]
	v_mfma_f32_16x16x32_bf16 v[124:127], v[148:151], v[188:191], v[124:127]
	v_mfma_f32_16x16x32_bf16 v[120:123], v[164:167], v[188:191], v[120:123]
	v_mfma_f32_16x16x32_bf16 v[108:111], v[148:151], v[196:199], v[108:111]
	v_mfma_f32_16x16x32_bf16 v[104:107], v[164:167], v[196:199], v[104:107]
	v_mfma_f32_16x16x32_bf16 v[92:95], v[148:151], v[204:207], v[92:95]
	v_mfma_f32_16x16x32_bf16 v[88:91], v[164:167], v[204:207], v[88:91]
	v_mfma_f32_16x16x32_bf16 v[76:79], v[148:151], v[212:215], v[76:79]
	v_mfma_f32_16x16x32_bf16 v[72:75], v[164:167], v[212:215], v[72:75]
	v_mfma_f32_16x16x32_bf16 v[116:119], v[168:171], v[184:187], v[116:119]
	v_mfma_f32_16x16x32_bf16 v[112:115], v[176:179], v[184:187], v[112:115]
	v_mfma_f32_16x16x32_bf16 v[100:103], v[168:171], v[192:195], v[100:103]
	v_mfma_f32_16x16x32_bf16 v[96:99], v[176:179], v[192:195], v[96:99]
	v_mfma_f32_16x16x32_bf16 v[84:87], v[168:171], v[200:203], v[84:87]
	v_mfma_f32_16x16x32_bf16 v[80:83], v[176:179], v[200:203], v[80:83]
	v_mfma_f32_16x16x32_bf16 v[68:71], v[168:171], v[208:211], v[68:71]
	v_mfma_f32_16x16x32_bf16 v[64:67], v[176:179], v[208:211], v[64:67]
	v_mfma_f32_16x16x32_bf16 v[116:119], v[172:175], v[188:191], v[116:119]
	v_mfma_f32_16x16x32_bf16 v[112:115], v[180:183], v[188:191], v[112:115]
	v_mfma_f32_16x16x32_bf16 v[100:103], v[172:175], v[196:199], v[100:103]
	v_mfma_f32_16x16x32_bf16 v[96:99], v[180:183], v[196:199], v[96:99]
	v_mfma_f32_16x16x32_bf16 v[84:87], v[172:175], v[204:207], v[84:87]
	v_mfma_f32_16x16x32_bf16 v[80:83], v[180:183], v[204:207], v[80:83]
	v_mfma_f32_16x16x32_bf16 v[68:71], v[172:175], v[212:215], v[68:71]
	v_mfma_f32_16x16x32_bf16 v[64:67], v[180:183], v[212:215], v[64:67]
	s_barrier
	ds_read_b128 v[184:187], v163 offset:49152
	ds_read_b128 v[188:191], v163 offset:50176
	ds_read_b128 v[192:195], v163 offset:51200
	ds_read_b128 v[196:199], v163 offset:52224
	ds_read_b128 v[200:203], v163 offset:53248
	ds_read_b128 v[204:207], v163 offset:54272
	ds_read_b128 v[208:211], v163 offset:55296
	ds_read_b128 v[212:215], v163 offset:56320
	s_add_i32 s8, s66, s21
	v_lshl_add_u64 v[228:229], v[216:217], 0, s[36:37]
	s_mov_b32 m0, s8
	s_nop 0
	global_load_lds_dwordx4 v[228:229], off
	s_add_i32 m0, s8, 0x2000
	s_add_u32 s8, s46, 0x160080
	v_lshl_add_u64 v[228:229], v[218:219], 0, s[36:37]
	s_addc_u32 s9, s47, 0
	s_add_i32 s46, s67, s21
	global_load_lds_dwordx4 v[228:229], off
	v_lshl_add_u64 v[228:229], s[8:9], 0, v[130:131]
	s_mov_b32 m0, s46
	s_nop 0
	global_load_lds_dwordx4 v[228:229], off
	v_lshl_add_u64 v[228:229], s[8:9], 0, v[134:135]
	s_add_i32 m0, s46, 0x2000
	s_nop 0
	global_load_lds_dwordx4 v[228:229], off
	v_lshl_add_u64 v[228:229], v[220:221], 0, s[36:37]
	s_mov_b32 m0, s26
	s_nop 0
	global_load_lds_dwordx4 v[228:229], off
	v_lshl_add_u64 v[228:229], v[222:223], 0, s[36:37]
	s_mov_b32 m0, s27
	s_nop 0
	global_load_lds_dwordx4 v[228:229], off
	s_waitcnt vmcnt(8)
	s_waitcnt lgkmcnt(0)
	s_barrier
	s_waitcnt lgkmcnt(0)
	v_mfma_f32_16x16x32_bf16 v[60:63], v[144:147], v[184:187], v[60:63]
	v_mfma_f32_16x16x32_bf16 v[56:59], v[152:155], v[184:187], v[56:59]
	v_mfma_f32_16x16x32_bf16 v[44:47], v[144:147], v[192:195], v[44:47]
	v_mfma_f32_16x16x32_bf16 v[40:43], v[152:155], v[192:195], v[40:43]
	v_mfma_f32_16x16x32_bf16 v[28:31], v[144:147], v[200:203], v[28:31]
	v_mfma_f32_16x16x32_bf16 v[24:27], v[152:155], v[200:203], v[24:27]
	v_mfma_f32_16x16x32_bf16 v[12:15], v[144:147], v[208:211], v[12:15]
	v_mfma_f32_16x16x32_bf16 v[8:11], v[152:155], v[208:211], v[8:11]
	v_mfma_f32_16x16x32_bf16 v[60:63], v[148:151], v[188:191], v[60:63]
	v_mfma_f32_16x16x32_bf16 v[56:59], v[164:167], v[188:191], v[56:59]
	v_mfma_f32_16x16x32_bf16 v[44:47], v[148:151], v[196:199], v[44:47]
	v_mfma_f32_16x16x32_bf16 v[40:43], v[164:167], v[196:199], v[40:43]
	v_mfma_f32_16x16x32_bf16 v[28:31], v[148:151], v[204:207], v[28:31]
	v_mfma_f32_16x16x32_bf16 v[24:27], v[164:167], v[204:207], v[24:27]
	v_mfma_f32_16x16x32_bf16 v[12:15], v[148:151], v[212:215], v[12:15]
	v_mfma_f32_16x16x32_bf16 v[8:11], v[164:167], v[212:215], v[8:11]
	v_mfma_f32_16x16x32_bf16 v[52:55], v[168:171], v[184:187], v[52:55]
	v_mfma_f32_16x16x32_bf16 v[48:51], v[176:179], v[184:187], v[48:51]
	v_mfma_f32_16x16x32_bf16 v[36:39], v[168:171], v[192:195], v[36:39]
	v_mfma_f32_16x16x32_bf16 v[32:35], v[176:179], v[192:195], v[32:35]
	v_mfma_f32_16x16x32_bf16 v[20:23], v[168:171], v[200:203], v[20:23]
	v_mfma_f32_16x16x32_bf16 v[16:19], v[176:179], v[200:203], v[16:19]
	v_mfma_f32_16x16x32_bf16 v[4:7], v[168:171], v[208:211], v[4:7]
	v_mfma_f32_16x16x32_bf16 v[0:3], v[176:179], v[208:211], v[0:3]
	v_mfma_f32_16x16x32_bf16 v[52:55], v[172:175], v[188:191], v[52:55]
	v_mfma_f32_16x16x32_bf16 v[48:51], v[180:183], v[188:191], v[48:51]
	v_mfma_f32_16x16x32_bf16 v[36:39], v[172:175], v[196:199], v[36:39]
	v_mfma_f32_16x16x32_bf16 v[32:35], v[180:183], v[196:199], v[32:35]
	v_mfma_f32_16x16x32_bf16 v[20:23], v[172:175], v[204:207], v[20:23]
	v_mfma_f32_16x16x32_bf16 v[16:19], v[180:183], v[204:207], v[16:19]
	v_mfma_f32_16x16x32_bf16 v[4:7], v[172:175], v[212:215], v[4:7]
	v_mfma_f32_16x16x32_bf16 v[0:3], v[180:183], v[212:215], v[0:3]
	s_barrier
	s_add_i32 s65, s65, 2
	s_add_u32 s63, s63, 0x100
	s_addc_u32 s64, s64, 0
	s_cmpk_gt_u32 s65, 0x55
	s_mov_b64 s[8:9], s[6:7]
	s_cbranch_scc0 .LBB0_248
	s_setprio 0
	s_and_b64 vcc, exec, s[28:29]
	s_cbranch_vccz .LBB0_251
	s_barrier

.Lgprio2:
.LBB0_387:
	ds_read_b128 v[146:149], v156
	ds_read_b128 v[160:163], v156 offset:1024
	ds_read_b128 v[164:167], v156 offset:2048
	ds_read_b128 v[168:171], v156 offset:3072
	ds_read_b128 v[172:175], v157
	ds_read_b128 v[176:179], v157 offset:1024
	ds_read_b128 v[180:183], v157 offset:2048
	ds_read_b128 v[184:187], v157 offset:3072
	ds_read_b128 v[188:191], v158
	ds_read_b128 v[192:195], v158 offset:1024
	ds_read_b128 v[196:199], v158 offset:2048
	ds_read_b128 v[200:203], v158 offset:3072
	ds_read_b128 v[204:207], v158 offset:4096
	ds_read_b128 v[208:211], v158 offset:5120
	ds_read_b128 v[212:215], v158 offset:6144
	ds_read_b128 v[216:219], v158 offset:7168
	s_add_u32 s38, s36, 0x100
	s_addc_u32 s39, s37, 0
	s_cmp_eq_u32 s64, 28
	s_cselect_b32 s43, s29, s39
	s_cselect_b32 s42, s60, s38
	s_cselect_b32 s41, s19, s63
	s_cselect_b32 s40, s61, s62
	v_lshl_add_u64 v[150:151], s[36:37], 0, v[138:139]
	s_add_i32 m0, s46, 0xc000
	s_nop 0
	global_load_lds_dwordx4 v[150:151], off
	v_lshl_add_u64 v[150:151], s[36:37], 0, v[140:141]
	s_add_i32 m0, s46, 0xe000
	s_nop 0
	global_load_lds_dwordx4 v[150:151], off
	s_waitcnt vmcnt(8)
	s_waitcnt lgkmcnt(0)
	s_barrier
	s_waitcnt lgkmcnt(0)
	v_mfma_f32_16x16x32_bf16 v[124:127], v[146:149], v[188:191], v[124:127]
	v_mfma_f32_16x16x32_bf16 v[120:123], v[164:167], v[188:191], v[120:123]
	v_mfma_f32_16x16x32_bf16 v[108:111], v[146:149], v[196:199], v[108:111]
	v_mfma_f32_16x16x32_bf16 v[104:107], v[164:167], v[196:199], v[104:107]
	v_mfma_f32_16x16x32_bf16 v[92:95], v[146:149], v[204:207], v[92:95]
	v_mfma_f32_16x16x32_bf16 v[88:91], v[164:167], v[204:207], v[88:91]
	v_mfma_f32_16x16x32_bf16 v[76:79], v[146:149], v[212:215], v[76:79]
	v_mfma_f32_16x16x32_bf16 v[72:75], v[164:167], v[212:215], v[72:75]
	v_mfma_f32_16x16x32_bf16 v[124:127], v[160:163], v[192:195], v[124:127]
	v_mfma_f32_16x16x32_bf16 v[120:123], v[168:171], v[192:195], v[120:123]
	v_mfma_f32_16x16x32_bf16 v[108:111], v[160:163], v[200:203], v[108:111]
	v_mfma_f32_16x16x32_bf16 v[104:107], v[168:171], v[200:203], v[104:107]
	v_mfma_f32_16x16x32_bf16 v[92:95], v[160:163], v[208:211], v[92:95]
	v_mfma_f32_16x16x32_bf16 v[88:91], v[168:171], v[208:211], v[88:91]
	v_mfma_f32_16x16x32_bf16 v[76:79], v[160:163], v[216:219], v[76:79]
	v_mfma_f32_16x16x32_bf16 v[72:75], v[168:171], v[216:219], v[72:75]
	v_mfma_f32_16x16x32_bf16 v[116:119], v[172:175], v[188:191], v[116:119]
	v_mfma_f32_16x16x32_bf16 v[112:115], v[180:183], v[188:191], v[112:115]
	v_mfma_f32_16x16x32_bf16 v[100:103], v[172:175], v[196:199], v[100:103]
	v_mfma_f32_16x16x32_bf16 v[96:99], v[180:183], v[196:199], v[96:99]
	v_mfma_f32_16x16x32_bf16 v[84:87], v[172:175], v[204:207], v[84:87]
	v_mfma_f32_16x16x32_bf16 v[80:83], v[180:183], v[204:207], v[80:83]
	v_mfma_f32_16x16x32_bf16 v[68:71], v[172:175], v[212:215], v[68:71]
	v_mfma_f32_16x16x32_bf16 v[64:67], v[180:183], v[212:215], v[64:67]
	v_mfma_f32_16x16x32_bf16 v[116:119], v[176:179], v[192:195], v[116:119]
	v_mfma_f32_16x16x32_bf16 v[112:115], v[184:187], v[192:195], v[112:115]
	v_mfma_f32_16x16x32_bf16 v[100:103], v[176:179], v[200:203], v[100:103]
	v_mfma_f32_16x16x32_bf16 v[96:99], v[184:187], v[200:203], v[96:99]
	v_mfma_f32_16x16x32_bf16 v[84:87], v[176:179], v[208:211], v[84:87]
	v_mfma_f32_16x16x32_bf16 v[80:83], v[184:187], v[208:211], v[80:83]
	v_mfma_f32_16x16x32_bf16 v[68:71], v[176:179], v[216:219], v[68:71]
	v_mfma_f32_16x16x32_bf16 v[64:67], v[184:187], v[216:219], v[64:67]
	s_barrier
	ds_read_b128 v[188:191], v158 offset:16384
	ds_read_b128 v[192:195], v158 offset:17408
	ds_read_b128 v[196:199], v158 offset:18432
	ds_read_b128 v[200:203], v158 offset:19456
	ds_read_b128 v[204:207], v158 offset:20480
	ds_read_b128 v[208:211], v158 offset:21504
	ds_read_b128 v[212:215], v158 offset:22528
	ds_read_b128 v[216:219], v158 offset:23552
	s_add_i32 s36, s55, s11
	v_lshl_add_u64 v[150:151], s[40:41], 0, v[130:131]
	s_mov_b32 m0, s36
	v_lshl_add_u64 v[220:221], s[40:41], 0, v[134:135]
	global_load_lds_dwordx4 v[150:151], off
	s_add_i32 m0, s36, 0x2000
	s_add_u32 s36, s40, 0x80000
	s_addc_u32 s37, s41, 0
	s_add_i32 s65, s56, s11
	global_load_lds_dwordx4 v[220:221], off
	v_lshl_add_u64 v[228:229], s[36:37], 0, v[130:131]
	s_mov_b32 m0, s65
	v_lshl_add_u64 v[222:223], s[42:43], 0, v[128:129]
	global_load_lds_dwordx4 v[228:229], off
	v_lshl_add_u64 v[228:229], s[36:37], 0, v[134:135]
	s_add_i32 m0, s65, 0x2000
	v_lshl_add_u64 v[224:225], s[42:43], 0, v[132:133]
	global_load_lds_dwordx4 v[228:229], off
	s_mov_b32 m0, s46
	s_nop 0
	global_load_lds_dwordx4 v[222:223], off
	s_mov_b32 m0, s47
	s_nop 0
	global_load_lds_dwordx4 v[224:225], off
	s_waitcnt vmcnt(8)
	s_waitcnt lgkmcnt(0)
	s_barrier
	s_waitcnt lgkmcnt(0)
	v_mfma_f32_16x16x32_bf16 v[60:63], v[146:149], v[188:191], v[60:63]
	v_mfma_f32_16x16x32_bf16 v[56:59], v[164:167], v[188:191], v[56:59]
	v_mfma_f32_16x16x32_bf16 v[44:47], v[146:149], v[196:199], v[44:47]
	v_mfma_f32_16x16x32_bf16 v[40:43], v[164:167], v[196:199], v[40:43]
	v_mfma_f32_16x16x32_bf16 v[28:31], v[146:149], v[204:207], v[28:31]
	v_mfma_f32_16x16x32_bf16 v[24:27], v[164:167], v[204:207], v[24:27]
	v_mfma_f32_16x16x32_bf16 v[12:15], v[146:149], v[212:215], v[12:15]
	v_mfma_f32_16x16x32_bf16 v[8:11], v[164:167], v[212:215], v[8:11]
	v_mfma_f32_16x16x32_bf16 v[60:63], v[160:163], v[192:195], v[60:63]
	v_mfma_f32_16x16x32_bf16 v[56:59], v[168:171], v[192:195], v[56:59]
	v_mfma_f32_16x16x32_bf16 v[44:47], v[160:163], v[200:203], v[44:47]
	v_mfma_f32_16x16x32_bf16 v[40:43], v[168:171], v[200:203], v[40:43]
	v_mfma_f32_16x16x32_bf16 v[28:31], v[160:163], v[208:211], v[28:31]
	v_mfma_f32_16x16x32_bf16 v[24:27], v[168:171], v[208:211], v[24:27]
	v_mfma_f32_16x16x32_bf16 v[12:15], v[160:163], v[216:219], v[12:15]
	v_mfma_f32_16x16x32_bf16 v[8:11], v[168:171], v[216:219], v[8:11]
	v_mfma_f32_16x16x32_bf16 v[52:55], v[172:175], v[188:191], v[52:55]
	v_mfma_f32_16x16x32_bf16 v[48:51], v[180:183], v[188:191], v[48:51]
	v_mfma_f32_16x16x32_bf16 v[36:39], v[172:175], v[196:199], v[36:39]
	v_mfma_f32_16x16x32_bf16 v[32:35], v[180:183], v[196:199], v[32:35]
	v_mfma_f32_16x16x32_bf16 v[20:23], v[172:175], v[204:207], v[20:23]
	v_mfma_f32_16x16x32_bf16 v[16:19], v[180:183], v[204:207], v[16:19]
	v_mfma_f32_16x16x32_bf16 v[4:7], v[172:175], v[212:215], v[4:7]
	v_mfma_f32_16x16x32_bf16 v[0:3], v[180:183], v[212:215], v[0:3]
	v_mfma_f32_16x16x32_bf16 v[52:55], v[176:179], v[192:195], v[52:55]
	v_mfma_f32_16x16x32_bf16 v[48:51], v[184:187], v[192:195], v[48:51]
	v_mfma_f32_16x16x32_bf16 v[36:39], v[176:179], v[200:203], v[36:39]
	v_mfma_f32_16x16x32_bf16 v[32:35], v[184:187], v[200:203], v[32:35]
	v_mfma_f32_16x16x32_bf16 v[20:23], v[176:179], v[208:211], v[20:23]
	v_mfma_f32_16x16x32_bf16 v[16:19], v[184:187], v[208:211], v[16:19]
	v_mfma_f32_16x16x32_bf16 v[4:7], v[176:179], v[216:219], v[4:7]
	v_mfma_f32_16x16x32_bf16 v[0:3], v[184:187], v[216:219], v[0:3]
	s_barrier
	s_add_i32 s65, 0, 0x18000
	s_add_i32 s66, 0, 0x1c000
	v_add_u32_e32 v168, s65, v154
	v_add_u32_e32 v184, s66, v154
	ds_read_b128 v[146:149], v168
	ds_read_b128 v[160:163], v168 offset:1024
	ds_read_b128 v[164:167], v168 offset:2048
	ds_read_b128 v[168:171], v168 offset:3072
	ds_read_b128 v[172:175], v184
	ds_read_b128 v[176:179], v184 offset:1024
	ds_read_b128 v[180:183], v184 offset:2048
	ds_read_b128 v[184:187], v184 offset:3072
	ds_read_b128 v[188:191], v158 offset:32768
	ds_read_b128 v[192:195], v158 offset:33792
	ds_read_b128 v[196:199], v158 offset:34816
	ds_read_b128 v[200:203], v158 offset:35840
	ds_read_b128 v[204:207], v158 offset:36864
	ds_read_b128 v[208:211], v158 offset:37888
	ds_read_b128 v[212:215], v158 offset:38912
	ds_read_b128 v[216:219], v158 offset:39936
	s_add_u32 s36, s42, 0x80000
	s_addc_u32 s37, s43, 0
	s_mov_b32 m0, s48
	v_lshl_add_u64 v[228:229], s[36:37], 0, v[128:129]
	global_load_lds_dwordx4 v[228:229], off
	v_lshl_add_u64 v[228:229], s[36:37], 0, v[132:133]
	s_mov_b32 m0, s49
	s_nop 0
	global_load_lds_dwordx4 v[228:229], off
	s_waitcnt vmcnt(8)
	s_waitcnt lgkmcnt(0)
	s_barrier
	s_waitcnt lgkmcnt(0)
	v_mfma_f32_16x16x32_bf16 v[124:127], v[146:149], v[188:191], v[124:127]
	v_mfma_f32_16x16x32_bf16 v[120:123], v[164:167], v[188:191], v[120:123]
	v_mfma_f32_16x16x32_bf16 v[108:111], v[146:149], v[196:199], v[108:111]
	v_mfma_f32_16x16x32_bf16 v[104:107], v[164:167], v[196:199], v[104:107]
	v_mfma_f32_16x16x32_bf16 v[92:95], v[146:149], v[204:207], v[92:95]
	v_mfma_f32_16x16x32_bf16 v[88:91], v[164:167], v[204:207], v[88:91]
	v_mfma_f32_16x16x32_bf16 v[76:79], v[146:149], v[212:215], v[76:79]
	v_mfma_f32_16x16x32_bf16 v[72:75], v[164:167], v[212:215], v[72:75]
	v_mfma_f32_16x16x32_bf16 v[124:127], v[160:163], v[192:195], v[124:127]
	v_mfma_f32_16x16x32_bf16 v[120:123], v[168:171], v[192:195], v[120:123]
	v_mfma_f32_16x16x32_bf16 v[108:111], v[160:163], v[200:203], v[108:111]
	v_mfma_f32_16x16x32_bf16 v[104:107], v[168:171], v[200:203], v[104:107]
	v_mfma_f32_16x16x32_bf16 v[92:95], v[160:163], v[208:211], v[92:95]
	v_mfma_f32_16x16x32_bf16 v[88:91], v[168:171], v[208:211], v[88:91]
	v_mfma_f32_16x16x32_bf16 v[76:79], v[160:163], v[216:219], v[76:79]
	v_mfma_f32_16x16x32_bf16 v[72:75], v[168:171], v[216:219], v[72:75]
	v_mfma_f32_16x16x32_bf16 v[116:119], v[172:175], v[188:191], v[116:119]
	v_mfma_f32_16x16x32_bf16 v[112:115], v[180:183], v[188:191], v[112:115]
	v_mfma_f32_16x16x32_bf16 v[100:103], v[172:175], v[196:199], v[100:103]
	v_mfma_f32_16x16x32_bf16 v[96:99], v[180:183], v[196:199], v[96:99]
	v_mfma_f32_16x16x32_bf16 v[84:87], v[172:175], v[204:207], v[84:87]
	v_mfma_f32_16x16x32_bf16 v[80:83], v[180:183], v[204:207], v[80:83]
	v_mfma_f32_16x16x32_bf16 v[68:71], v[172:175], v[212:215], v[68:71]
	v_mfma_f32_16x16x32_bf16 v[64:67], v[180:183], v[212:215], v[64:67]
	v_mfma_f32_16x16x32_bf16 v[116:119], v[176:179], v[192:195], v[116:119]
	v_mfma_f32_16x16x32_bf16 v[112:115], v[184:187], v[192:195], v[112:115]
	v_mfma_f32_16x16x32_bf16 v[100:103], v[176:179], v[200:203], v[100:103]
	v_mfma_f32_16x16x32_bf16 v[96:99], v[184:187], v[200:203], v[96:99]
	v_mfma_f32_16x16x32_bf16 v[84:87], v[176:179], v[208:211], v[84:87]
	v_mfma_f32_16x16x32_bf16 v[80:83], v[184:187], v[208:211], v[80:83]
	v_mfma_f32_16x16x32_bf16 v[68:71], v[176:179], v[216:219], v[68:71]
	v_mfma_f32_16x16x32_bf16 v[64:67], v[184:187], v[216:219], v[64:67]
	s_barrier
	ds_read_b128 v[188:191], v158 offset:49152
	ds_read_b128 v[192:195], v158 offset:50176
	ds_read_b128 v[196:199], v158 offset:51200
	ds_read_b128 v[200:203], v158 offset:52224
	ds_read_b128 v[204:207], v158 offset:53248
	ds_read_b128 v[208:211], v158 offset:54272
	ds_read_b128 v[212:215], v158 offset:55296
	ds_read_b128 v[216:219], v158 offset:56320
	s_add_i32 s36, s65, s11
	v_lshl_add_u64 v[150:151], v[150:151], 0, s[14:15]
	s_mov_b32 m0, s36
	s_nop 0
	global_load_lds_dwordx4 v[150:151], off
	s_add_i32 m0, s36, 0x2000
	s_add_u32 s36, s40, 0x80080
	v_lshl_add_u64 v[150:151], v[220:221], 0, s[14:15]
	s_addc_u32 s37, s41, 0
	s_add_i32 s40, s66, s11
	global_load_lds_dwordx4 v[150:151], off
	v_lshl_add_u64 v[150:151], s[36:37], 0, v[130:131]
	s_mov_b32 m0, s40
	s_nop 0
	global_load_lds_dwordx4 v[150:151], off
	v_lshl_add_u64 v[150:151], s[36:37], 0, v[134:135]
	s_add_i32 m0, s40, 0x2000
	s_nop 0
	global_load_lds_dwordx4 v[150:151], off
	v_lshl_add_u64 v[150:151], v[222:223], 0, s[14:15]
	s_mov_b32 m0, s53
	s_nop 0
	global_load_lds_dwordx4 v[150:151], off
	v_lshl_add_u64 v[150:151], v[224:225], 0, s[14:15]
	s_mov_b32 m0, s54
	s_nop 0
	global_load_lds_dwordx4 v[150:151], off
	s_waitcnt vmcnt(8)
	s_waitcnt lgkmcnt(0)
	s_barrier
	s_waitcnt lgkmcnt(0)
	v_mfma_f32_16x16x32_bf16 v[60:63], v[146:149], v[188:191], v[60:63]
	v_mfma_f32_16x16x32_bf16 v[56:59], v[164:167], v[188:191], v[56:59]
	v_mfma_f32_16x16x32_bf16 v[44:47], v[146:149], v[196:199], v[44:47]
	v_mfma_f32_16x16x32_bf16 v[40:43], v[164:167], v[196:199], v[40:43]
	v_mfma_f32_16x16x32_bf16 v[28:31], v[146:149], v[204:207], v[28:31]
	v_mfma_f32_16x16x32_bf16 v[24:27], v[164:167], v[204:207], v[24:27]
	v_mfma_f32_16x16x32_bf16 v[12:15], v[146:149], v[212:215], v[12:15]
	v_mfma_f32_16x16x32_bf16 v[8:11], v[164:167], v[212:215], v[8:11]
	v_mfma_f32_16x16x32_bf16 v[60:63], v[160:163], v[192:195], v[60:63]
	v_mfma_f32_16x16x32_bf16 v[56:59], v[168:171], v[192:195], v[56:59]
	v_mfma_f32_16x16x32_bf16 v[44:47], v[160:163], v[200:203], v[44:47]
	v_mfma_f32_16x16x32_bf16 v[40:43], v[168:171], v[200:203], v[40:43]
	v_mfma_f32_16x16x32_bf16 v[28:31], v[160:163], v[208:211], v[28:31]
	v_mfma_f32_16x16x32_bf16 v[24:27], v[168:171], v[208:211], v[24:27]
	v_mfma_f32_16x16x32_bf16 v[12:15], v[160:163], v[216:219], v[12:15]
	v_mfma_f32_16x16x32_bf16 v[8:11], v[168:171], v[216:219], v[8:11]
	v_mfma_f32_16x16x32_bf16 v[52:55], v[172:175], v[188:191], v[52:55]
	v_mfma_f32_16x16x32_bf16 v[48:51], v[180:183], v[188:191], v[48:51]
	v_mfma_f32_16x16x32_bf16 v[36:39], v[172:175], v[196:199], v[36:39]
	v_mfma_f32_16x16x32_bf16 v[32:35], v[180:183], v[196:199], v[32:35]
	v_mfma_f32_16x16x32_bf16 v[20:23], v[172:175], v[204:207], v[20:23]
	v_mfma_f32_16x16x32_bf16 v[16:19], v[180:183], v[204:207], v[16:19]
	v_mfma_f32_16x16x32_bf16 v[4:7], v[172:175], v[212:215], v[4:7]
	v_mfma_f32_16x16x32_bf16 v[0:3], v[180:183], v[212:215], v[0:3]
	v_mfma_f32_16x16x32_bf16 v[52:55], v[176:179], v[192:195], v[52:55]
	v_mfma_f32_16x16x32_bf16 v[48:51], v[184:187], v[192:195], v[48:51]
	v_mfma_f32_16x16x32_bf16 v[36:39], v[176:179], v[200:203], v[36:39]
	v_mfma_f32_16x16x32_bf16 v[32:35], v[184:187], v[200:203], v[32:35]
	v_mfma_f32_16x16x32_bf16 v[20:23], v[176:179], v[208:211], v[20:23]
	v_mfma_f32_16x16x32_bf16 v[16:19], v[184:187], v[208:211], v[16:19]
	v_mfma_f32_16x16x32_bf16 v[4:7], v[176:179], v[216:219], v[4:7]
	v_mfma_f32_16x16x32_bf16 v[0:3], v[184:187], v[216:219], v[0:3]
	s_barrier
	s_add_i32 s64, s64, 2
	s_add_u32 s62, s62, 0x100
	s_addc_u32 s63, s63, 0
	s_cmp_gt_u32 s64, 29
	s_mov_b64 s[36:37], s[38:39]
	s_cbranch_scc0 .LBB0_387
	s_setprio 0
	s_and_b64 vcc, exec, s[4:5]
	s_cbranch_vccnz .LBB0_392
	s_cmp_gt_i32 s59, 11
	s_mov_b64 s[36:37], -1
	s_cbranch_scc1 .LBB0_393

.Lgprio3:
.LBB0_1117:
	ds_read_b128 v[144:147], v159
	ds_read_b128 v[148:151], v159 offset:1024
	ds_read_b128 v[162:165], v159 offset:2048
	ds_read_b128 v[166:169], v159 offset:3072
	ds_read_b128 v[170:173], v160
	ds_read_b128 v[174:177], v160 offset:1024
	ds_read_b128 v[178:181], v160 offset:2048
	ds_read_b128 v[182:185], v160 offset:3072
	ds_read_b128 v[186:189], v161
	ds_read_b128 v[190:193], v161 offset:1024
	ds_read_b128 v[194:197], v161 offset:2048
	ds_read_b128 v[198:201], v161 offset:3072
	ds_read_b128 v[202:205], v161 offset:4096
	ds_read_b128 v[206:209], v161 offset:5120
	ds_read_b128 v[210:213], v161 offset:6144
	ds_read_b128 v[214:217], v161 offset:7168
	s_add_u32 s48, s46, 0xfff80080
	s_addc_u32 s49, s47, -1
	s_cmp_eq_u32 s63, 28
	s_cselect_b32 s51, s7, s49
	s_cselect_b32 s50, s11, s48
	s_cselect_b32 s49, s37, s62
	s_cselect_b32 s48, s39, s45
	v_lshl_add_u64 v[152:153], s[46:47], 0, v[136:137]
	s_add_i32 m0, s55, 0xc000
	s_nop 0
	global_load_lds_dwordx4 v[152:153], off
	v_lshl_add_u64 v[152:153], s[46:47], 0, v[138:139]
	s_add_i32 m0, s55, 0xe000
	s_nop 0
	global_load_lds_dwordx4 v[152:153], off
	s_waitcnt vmcnt(8)
	s_waitcnt lgkmcnt(0)
	s_barrier
	s_waitcnt lgkmcnt(0)
	v_mfma_f32_16x16x32_bf16 v[124:127], v[144:147], v[186:189], v[124:127]
	v_mfma_f32_16x16x32_bf16 v[120:123], v[162:165], v[186:189], v[120:123]
	v_mfma_f32_16x16x32_bf16 v[108:111], v[144:147], v[194:197], v[108:111]
	v_mfma_f32_16x16x32_bf16 v[104:107], v[162:165], v[194:197], v[104:107]
	v_mfma_f32_16x16x32_bf16 v[92:95], v[144:147], v[202:205], v[92:95]
	v_mfma_f32_16x16x32_bf16 v[88:91], v[162:165], v[202:205], v[88:91]
	v_mfma_f32_16x16x32_bf16 v[76:79], v[144:147], v[210:213], v[76:79]
	v_mfma_f32_16x16x32_bf16 v[72:75], v[162:165], v[210:213], v[72:75]
	v_mfma_f32_16x16x32_bf16 v[124:127], v[148:151], v[190:193], v[124:127]
	v_mfma_f32_16x16x32_bf16 v[120:123], v[166:169], v[190:193], v[120:123]
	v_mfma_f32_16x16x32_bf16 v[108:111], v[148:151], v[198:201], v[108:111]
	v_mfma_f32_16x16x32_bf16 v[104:107], v[166:169], v[198:201], v[104:107]
	v_mfma_f32_16x16x32_bf16 v[92:95], v[148:151], v[206:209], v[92:95]
	v_mfma_f32_16x16x32_bf16 v[88:91], v[166:169], v[206:209], v[88:91]
	v_mfma_f32_16x16x32_bf16 v[76:79], v[148:151], v[214:217], v[76:79]
	v_mfma_f32_16x16x32_bf16 v[72:75], v[166:169], v[214:217], v[72:75]
	v_mfma_f32_16x16x32_bf16 v[116:119], v[170:173], v[186:189], v[116:119]
	v_mfma_f32_16x16x32_bf16 v[112:115], v[178:181], v[186:189], v[112:115]
	v_mfma_f32_16x16x32_bf16 v[100:103], v[170:173], v[194:197], v[100:103]
	v_mfma_f32_16x16x32_bf16 v[96:99], v[178:181], v[194:197], v[96:99]
	v_mfma_f32_16x16x32_bf16 v[84:87], v[170:173], v[202:205], v[84:87]
	v_mfma_f32_16x16x32_bf16 v[80:83], v[178:181], v[202:205], v[80:83]
	v_mfma_f32_16x16x32_bf16 v[68:71], v[170:173], v[210:213], v[68:71]
	v_mfma_f32_16x16x32_bf16 v[64:67], v[178:181], v[210:213], v[64:67]
	v_mfma_f32_16x16x32_bf16 v[116:119], v[174:177], v[190:193], v[116:119]
	v_mfma_f32_16x16x32_bf16 v[112:115], v[182:185], v[190:193], v[112:115]
	v_mfma_f32_16x16x32_bf16 v[100:103], v[174:177], v[198:201], v[100:103]
	v_mfma_f32_16x16x32_bf16 v[96:99], v[182:185], v[198:201], v[96:99]
	v_mfma_f32_16x16x32_bf16 v[84:87], v[174:177], v[206:209], v[84:87]
	v_mfma_f32_16x16x32_bf16 v[80:83], v[182:185], v[206:209], v[80:83]
	v_mfma_f32_16x16x32_bf16 v[68:71], v[174:177], v[214:217], v[68:71]
	v_mfma_f32_16x16x32_bf16 v[64:67], v[182:185], v[214:217], v[64:67]
	s_barrier
	ds_read_b128 v[186:189], v161 offset:16384
	ds_read_b128 v[190:193], v161 offset:17408
	ds_read_b128 v[194:197], v161 offset:18432
	ds_read_b128 v[198:201], v161 offset:19456
	ds_read_b128 v[202:205], v161 offset:20480
	ds_read_b128 v[206:209], v161 offset:21504
	ds_read_b128 v[210:213], v161 offset:22528
	ds_read_b128 v[214:217], v161 offset:23552
	s_add_i32 s64, s60, s21
	v_lshl_add_u64 v[152:153], s[48:49], 0, v[130:131]
	s_mov_b32 m0, s64
	v_lshl_add_u64 v[218:219], s[48:49], 0, v[134:135]
	global_load_lds_dwordx4 v[152:153], off
	s_add_i32 m0, s64, 0x2000
	s_add_u32 s64, s48, 0x80000
	s_addc_u32 s65, s49, 0
	s_add_i32 s66, s61, s21
	global_load_lds_dwordx4 v[218:219], off
	v_lshl_add_u64 v[228:229], s[64:65], 0, v[130:131]
	s_mov_b32 m0, s66
	v_lshl_add_u64 v[220:221], s[50:51], 0, v[128:129]
	global_load_lds_dwordx4 v[228:229], off
	v_lshl_add_u64 v[228:229], s[64:65], 0, v[134:135]
	s_add_i32 m0, s66, 0x2000
	v_lshl_add_u64 v[222:223], s[50:51], 0, v[132:133]
	global_load_lds_dwordx4 v[228:229], off
	s_mov_b32 m0, s55
	s_nop 0
	global_load_lds_dwordx4 v[220:221], off
	s_mov_b32 m0, s56
	s_nop 0
	global_load_lds_dwordx4 v[222:223], off
	s_waitcnt vmcnt(8)
	s_waitcnt lgkmcnt(0)
	s_barrier
	s_waitcnt lgkmcnt(0)
	v_mfma_f32_16x16x32_bf16 v[60:63], v[144:147], v[186:189], v[60:63]
	v_mfma_f32_16x16x32_bf16 v[56:59], v[162:165], v[186:189], v[56:59]
	v_mfma_f32_16x16x32_bf16 v[44:47], v[144:147], v[194:197], v[44:47]
	v_mfma_f32_16x16x32_bf16 v[40:43], v[162:165], v[194:197], v[40:43]
	v_mfma_f32_16x16x32_bf16 v[28:31], v[144:147], v[202:205], v[28:31]
	v_mfma_f32_16x16x32_bf16 v[24:27], v[162:165], v[202:205], v[24:27]
	v_mfma_f32_16x16x32_bf16 v[12:15], v[144:147], v[210:213], v[12:15]
	v_mfma_f32_16x16x32_bf16 v[8:11], v[162:165], v[210:213], v[8:11]
	v_mfma_f32_16x16x32_bf16 v[60:63], v[148:151], v[190:193], v[60:63]
	v_mfma_f32_16x16x32_bf16 v[56:59], v[166:169], v[190:193], v[56:59]
	v_mfma_f32_16x16x32_bf16 v[44:47], v[148:151], v[198:201], v[44:47]
	v_mfma_f32_16x16x32_bf16 v[40:43], v[166:169], v[198:201], v[40:43]
	v_mfma_f32_16x16x32_bf16 v[28:31], v[148:151], v[206:209], v[28:31]
	v_mfma_f32_16x16x32_bf16 v[24:27], v[166:169], v[206:209], v[24:27]
	v_mfma_f32_16x16x32_bf16 v[12:15], v[148:151], v[214:217], v[12:15]
	v_mfma_f32_16x16x32_bf16 v[8:11], v[166:169], v[214:217], v[8:11]
	v_mfma_f32_16x16x32_bf16 v[52:55], v[170:173], v[186:189], v[52:55]
	v_mfma_f32_16x16x32_bf16 v[48:51], v[178:181], v[186:189], v[48:51]
	v_mfma_f32_16x16x32_bf16 v[36:39], v[170:173], v[194:197], v[36:39]
	v_mfma_f32_16x16x32_bf16 v[32:35], v[178:181], v[194:197], v[32:35]
	v_mfma_f32_16x16x32_bf16 v[20:23], v[170:173], v[202:205], v[20:23]
	v_mfma_f32_16x16x32_bf16 v[16:19], v[178:181], v[202:205], v[16:19]
	v_mfma_f32_16x16x32_bf16 v[4:7], v[170:173], v[210:213], v[4:7]
	v_mfma_f32_16x16x32_bf16 v[0:3], v[178:181], v[210:213], v[0:3]
	v_mfma_f32_16x16x32_bf16 v[52:55], v[174:177], v[190:193], v[52:55]
	v_mfma_f32_16x16x32_bf16 v[48:51], v[182:185], v[190:193], v[48:51]
	v_mfma_f32_16x16x32_bf16 v[36:39], v[174:177], v[198:201], v[36:39]
	v_mfma_f32_16x16x32_bf16 v[32:35], v[182:185], v[198:201], v[32:35]
	v_mfma_f32_16x16x32_bf16 v[20:23], v[174:177], v[206:209], v[20:23]
	v_mfma_f32_16x16x32_bf16 v[16:19], v[182:185], v[206:209], v[16:19]
	v_mfma_f32_16x16x32_bf16 v[4:7], v[174:177], v[214:217], v[4:7]
	v_mfma_f32_16x16x32_bf16 v[0:3], v[182:185], v[214:217], v[0:3]
	s_barrier
	s_add_i32 s64, 0, 0x18000
	s_add_i32 s65, 0, 0x1c000
	v_add_u32_e32 v166, s64, v154
	v_add_u32_e32 v182, s65, v154
	ds_read_b128 v[144:147], v166
	ds_read_b128 v[148:151], v166 offset:1024
	ds_read_b128 v[162:165], v166 offset:2048
	ds_read_b128 v[166:169], v166 offset:3072
	ds_read_b128 v[170:173], v182
	ds_read_b128 v[174:177], v182 offset:1024
	ds_read_b128 v[178:181], v182 offset:2048
	ds_read_b128 v[182:185], v182 offset:3072
	ds_read_b128 v[186:189], v161 offset:32768
	ds_read_b128 v[190:193], v161 offset:33792
	ds_read_b128 v[194:197], v161 offset:34816
	ds_read_b128 v[198:201], v161 offset:35840
	ds_read_b128 v[202:205], v161 offset:36864
	ds_read_b128 v[206:209], v161 offset:37888
	ds_read_b128 v[210:213], v161 offset:38912
	ds_read_b128 v[214:217], v161 offset:39936
	s_add_u32 s50, s50, 0x80000
	s_addc_u32 s51, s51, 0
	s_mov_b32 m0, s57
	v_lshl_add_u64 v[228:229], s[50:51], 0, v[128:129]
	global_load_lds_dwordx4 v[228:229], off
	v_lshl_add_u64 v[228:229], s[50:51], 0, v[132:133]
	s_mov_b32 m0, s58
	s_nop 0
	global_load_lds_dwordx4 v[228:229], off
	s_waitcnt vmcnt(8)
	s_waitcnt lgkmcnt(0)
	s_barrier
	s_waitcnt lgkmcnt(0)
	v_mfma_f32_16x16x32_bf16 v[124:127], v[144:147], v[186:189], v[124:127]
	v_mfma_f32_16x16x32_bf16 v[120:123], v[162:165], v[186:189], v[120:123]
	v_mfma_f32_16x16x32_bf16 v[108:111], v[144:147], v[194:197], v[108:111]
	v_mfma_f32_16x16x32_bf16 v[104:107], v[162:165], v[194:197], v[104:107]
	v_mfma_f32_16x16x32_bf16 v[92:95], v[144:147], v[202:205], v[92:95]
	v_mfma_f32_16x16x32_bf16 v[88:91], v[162:165], v[202:205], v[88:91]
	v_mfma_f32_16x16x32_bf16 v[76:79], v[144:147], v[210:213], v[76:79]
	v_mfma_f32_16x16x32_bf16 v[72:75], v[162:165], v[210:213], v[72:75]
	v_mfma_f32_16x16x32_bf16 v[124:127], v[148:151], v[190:193], v[124:127]
	v_mfma_f32_16x16x32_bf16 v[120:123], v[166:169], v[190:193], v[120:123]
	v_mfma_f32_16x16x32_bf16 v[108:111], v[148:151], v[198:201], v[108:111]
	v_mfma_f32_16x16x32_bf16 v[104:107], v[166:169], v[198:201], v[104:107]
	v_mfma_f32_16x16x32_bf16 v[92:95], v[148:151], v[206:209], v[92:95]
	v_mfma_f32_16x16x32_bf16 v[88:91], v[166:169], v[206:209], v[88:91]
	v_mfma_f32_16x16x32_bf16 v[76:79], v[148:151], v[214:217], v[76:79]
	v_mfma_f32_16x16x32_bf16 v[72:75], v[166:169], v[214:217], v[72:75]
	v_mfma_f32_16x16x32_bf16 v[116:119], v[170:173], v[186:189], v[116:119]
	v_mfma_f32_16x16x32_bf16 v[112:115], v[178:181], v[186:189], v[112:115]
	v_mfma_f32_16x16x32_bf16 v[100:103], v[170:173], v[194:197], v[100:103]
	v_mfma_f32_16x16x32_bf16 v[96:99], v[178:181], v[194:197], v[96:99]
	v_mfma_f32_16x16x32_bf16 v[84:87], v[170:173], v[202:205], v[84:87]
	v_mfma_f32_16x16x32_bf16 v[80:83], v[178:181], v[202:205], v[80:83]
	v_mfma_f32_16x16x32_bf16 v[68:71], v[170:173], v[210:213], v[68:71]
	v_mfma_f32_16x16x32_bf16 v[64:67], v[178:181], v[210:213], v[64:67]
	v_mfma_f32_16x16x32_bf16 v[116:119], v[174:177], v[190:193], v[116:119]
	v_mfma_f32_16x16x32_bf16 v[112:115], v[182:185], v[190:193], v[112:115]
	v_mfma_f32_16x16x32_bf16 v[100:103], v[174:177], v[198:201], v[100:103]
	v_mfma_f32_16x16x32_bf16 v[96:99], v[182:185], v[198:201], v[96:99]
	v_mfma_f32_16x16x32_bf16 v[84:87], v[174:177], v[206:209], v[84:87]
	v_mfma_f32_16x16x32_bf16 v[80:83], v[182:185], v[206:209], v[80:83]
	v_mfma_f32_16x16x32_bf16 v[68:71], v[174:177], v[214:217], v[68:71]
	v_mfma_f32_16x16x32_bf16 v[64:67], v[182:185], v[214:217], v[64:67]
	s_barrier
	ds_read_b128 v[186:189], v161 offset:49152
	ds_read_b128 v[190:193], v161 offset:50176
	ds_read_b128 v[194:197], v161 offset:51200
	ds_read_b128 v[198:201], v161 offset:52224
	ds_read_b128 v[202:205], v161 offset:53248
	ds_read_b128 v[206:209], v161 offset:54272
	ds_read_b128 v[210:213], v161 offset:55296
	ds_read_b128 v[214:217], v161 offset:56320
	s_add_i32 s50, s64, s21
	v_lshl_add_u64 v[152:153], v[152:153], 0, s[30:31]
	s_mov_b32 m0, s50
	s_nop 0
	global_load_lds_dwordx4 v[152:153], off
	s_add_i32 m0, s50, 0x2000
	s_add_u32 s48, s48, 0x80080
	v_lshl_add_u64 v[152:153], v[218:219], 0, s[30:31]
	s_addc_u32 s49, s49, 0
	s_add_i32 s50, s65, s21
	global_load_lds_dwordx4 v[152:153], off
	v_lshl_add_u64 v[152:153], s[48:49], 0, v[130:131]
	s_mov_b32 m0, s50
	s_nop 0
	global_load_lds_dwordx4 v[152:153], off
	v_lshl_add_u64 v[152:153], s[48:49], 0, v[134:135]
	s_add_i32 m0, s50, 0x2000
	s_nop 0
	global_load_lds_dwordx4 v[152:153], off
	v_lshl_add_u64 v[152:153], v[220:221], 0, s[30:31]
	s_mov_b32 m0, s26
	s_nop 0
	global_load_lds_dwordx4 v[152:153], off
	v_lshl_add_u64 v[152:153], v[222:223], 0, s[30:31]
	s_mov_b32 m0, s27
	s_nop 0
	global_load_lds_dwordx4 v[152:153], off
	s_waitcnt vmcnt(8)
	s_waitcnt lgkmcnt(0)
	s_barrier
	s_waitcnt lgkmcnt(0)
	v_mfma_f32_16x16x32_bf16 v[60:63], v[144:147], v[186:189], v[60:63]
	v_mfma_f32_16x16x32_bf16 v[56:59], v[162:165], v[186:189], v[56:59]
	v_mfma_f32_16x16x32_bf16 v[44:47], v[144:147], v[194:197], v[44:47]
	v_mfma_f32_16x16x32_bf16 v[40:43], v[162:165], v[194:197], v[40:43]
	v_mfma_f32_16x16x32_bf16 v[28:31], v[144:147], v[202:205], v[28:31]
	v_mfma_f32_16x16x32_bf16 v[24:27], v[162:165], v[202:205], v[24:27]
	v_mfma_f32_16x16x32_bf16 v[12:15], v[144:147], v[210:213], v[12:15]
	v_mfma_f32_16x16x32_bf16 v[8:11], v[162:165], v[210:213], v[8:11]
	v_mfma_f32_16x16x32_bf16 v[60:63], v[148:151], v[190:193], v[60:63]
	v_mfma_f32_16x16x32_bf16 v[56:59], v[166:169], v[190:193], v[56:59]
	v_mfma_f32_16x16x32_bf16 v[44:47], v[148:151], v[198:201], v[44:47]
	v_mfma_f32_16x16x32_bf16 v[40:43], v[166:169], v[198:201], v[40:43]
	v_mfma_f32_16x16x32_bf16 v[28:31], v[148:151], v[206:209], v[28:31]
	v_mfma_f32_16x16x32_bf16 v[24:27], v[166:169], v[206:209], v[24:27]
	v_mfma_f32_16x16x32_bf16 v[12:15], v[148:151], v[214:217], v[12:15]
	v_mfma_f32_16x16x32_bf16 v[8:11], v[166:169], v[214:217], v[8:11]
	v_mfma_f32_16x16x32_bf16 v[52:55], v[170:173], v[186:189], v[52:55]
	v_mfma_f32_16x16x32_bf16 v[48:51], v[178:181], v[186:189], v[48:51]
	v_mfma_f32_16x16x32_bf16 v[36:39], v[170:173], v[194:197], v[36:39]
	v_mfma_f32_16x16x32_bf16 v[32:35], v[178:181], v[194:197], v[32:35]
	v_mfma_f32_16x16x32_bf16 v[20:23], v[170:173], v[202:205], v[20:23]
	v_mfma_f32_16x16x32_bf16 v[16:19], v[178:181], v[202:205], v[16:19]
	v_mfma_f32_16x16x32_bf16 v[4:7], v[170:173], v[210:213], v[4:7]
	v_mfma_f32_16x16x32_bf16 v[0:3], v[178:181], v[210:213], v[0:3]
	v_mfma_f32_16x16x32_bf16 v[52:55], v[174:177], v[190:193], v[52:55]
	v_mfma_f32_16x16x32_bf16 v[48:51], v[182:185], v[190:193], v[48:51]
	v_mfma_f32_16x16x32_bf16 v[36:39], v[174:177], v[198:201], v[36:39]
	v_mfma_f32_16x16x32_bf16 v[32:35], v[182:185], v[198:201], v[32:35]
	v_mfma_f32_16x16x32_bf16 v[20:23], v[174:177], v[206:209], v[20:23]
	v_mfma_f32_16x16x32_bf16 v[16:19], v[182:185], v[206:209], v[16:19]
	v_mfma_f32_16x16x32_bf16 v[4:7], v[174:177], v[214:217], v[4:7]
	v_mfma_f32_16x16x32_bf16 v[0:3], v[182:185], v[214:217], v[0:3]
	s_barrier
	s_add_i32 s63, s63, 2
	s_add_u32 s46, s46, 0x100
	s_addc_u32 s47, s47, 0
	s_add_u32 s45, s45, 0x100
	s_addc_u32 s62, s62, 0
	s_cmp_gt_u32 s63, 29
	s_cbranch_scc0 .LBB0_1117
	s_setprio 0
	s_and_b64 vcc, exec, s[16:17]
	s_cbranch_vccz .LBB0_1120
	s_barrier

.Lgprio4:
.LBB0_1240:
	ds_read_b128 v[144:147], v153
	ds_read_b128 v[158:161], v153 offset:1024
	ds_read_b128 v[162:165], v153 offset:2048
	ds_read_b128 v[166:169], v153 offset:3072
	ds_read_b128 v[170:173], v154
	ds_read_b128 v[174:177], v154 offset:1024
	ds_read_b128 v[178:181], v154 offset:2048
	ds_read_b128 v[182:185], v154 offset:3072
	ds_read_b128 v[186:189], v155
	ds_read_b128 v[190:193], v155 offset:1024
	ds_read_b128 v[194:197], v155 offset:2048
	ds_read_b128 v[198:201], v155 offset:3072
	ds_read_b128 v[202:205], v155 offset:4096
	ds_read_b128 v[206:209], v155 offset:5120
	ds_read_b128 v[210:213], v155 offset:6144
	ds_read_b128 v[214:217], v155 offset:7168
	s_add_u32 s40, s38, 0x100
	s_addc_u32 s41, s39, 0
	s_cmp_eq_u32 s61, 28
	s_cselect_b32 s45, s29, s41
	s_cselect_b32 s44, s57, s40
	s_cselect_b32 s43, s19, s60
	s_cselect_b32 s42, s58, s59
	v_lshl_add_u64 v[148:149], s[38:39], 0, v[136:137]
	s_add_i32 m0, s37, 0xc000
	s_nop 0
	global_load_lds_dwordx4 v[148:149], off
	v_lshl_add_u64 v[148:149], s[38:39], 0, v[138:139]
	s_add_i32 m0, s37, 0xe000
	s_nop 0
	global_load_lds_dwordx4 v[148:149], off
	s_waitcnt vmcnt(8)
	s_waitcnt lgkmcnt(0)
	s_barrier
	s_waitcnt lgkmcnt(0)
	v_mfma_f32_16x16x32_bf16 v[124:127], v[144:147], v[186:189], v[124:127]
	v_mfma_f32_16x16x32_bf16 v[120:123], v[162:165], v[186:189], v[120:123]
	v_mfma_f32_16x16x32_bf16 v[108:111], v[144:147], v[194:197], v[108:111]
	v_mfma_f32_16x16x32_bf16 v[104:107], v[162:165], v[194:197], v[104:107]
	v_mfma_f32_16x16x32_bf16 v[92:95], v[144:147], v[202:205], v[92:95]
	v_mfma_f32_16x16x32_bf16 v[88:91], v[162:165], v[202:205], v[88:91]
	v_mfma_f32_16x16x32_bf16 v[76:79], v[144:147], v[210:213], v[76:79]
	v_mfma_f32_16x16x32_bf16 v[72:75], v[162:165], v[210:213], v[72:75]
	v_mfma_f32_16x16x32_bf16 v[124:127], v[158:161], v[190:193], v[124:127]
	v_mfma_f32_16x16x32_bf16 v[120:123], v[166:169], v[190:193], v[120:123]
	v_mfma_f32_16x16x32_bf16 v[108:111], v[158:161], v[198:201], v[108:111]
	v_mfma_f32_16x16x32_bf16 v[104:107], v[166:169], v[198:201], v[104:107]
	v_mfma_f32_16x16x32_bf16 v[92:95], v[158:161], v[206:209], v[92:95]
	v_mfma_f32_16x16x32_bf16 v[88:91], v[166:169], v[206:209], v[88:91]
	v_mfma_f32_16x16x32_bf16 v[76:79], v[158:161], v[214:217], v[76:79]
	v_mfma_f32_16x16x32_bf16 v[72:75], v[166:169], v[214:217], v[72:75]
	v_mfma_f32_16x16x32_bf16 v[116:119], v[170:173], v[186:189], v[116:119]
	v_mfma_f32_16x16x32_bf16 v[112:115], v[178:181], v[186:189], v[112:115]
	v_mfma_f32_16x16x32_bf16 v[100:103], v[170:173], v[194:197], v[100:103]
	v_mfma_f32_16x16x32_bf16 v[96:99], v[178:181], v[194:197], v[96:99]
	v_mfma_f32_16x16x32_bf16 v[84:87], v[170:173], v[202:205], v[84:87]
	v_mfma_f32_16x16x32_bf16 v[80:83], v[178:181], v[202:205], v[80:83]
	v_mfma_f32_16x16x32_bf16 v[68:71], v[170:173], v[210:213], v[68:71]
	v_mfma_f32_16x16x32_bf16 v[64:67], v[178:181], v[210:213], v[64:67]
	v_mfma_f32_16x16x32_bf16 v[116:119], v[174:177], v[190:193], v[116:119]
	v_mfma_f32_16x16x32_bf16 v[112:115], v[182:185], v[190:193], v[112:115]
	v_mfma_f32_16x16x32_bf16 v[100:103], v[174:177], v[198:201], v[100:103]
	v_mfma_f32_16x16x32_bf16 v[96:99], v[182:185], v[198:201], v[96:99]
	v_mfma_f32_16x16x32_bf16 v[84:87], v[174:177], v[206:209], v[84:87]
	v_mfma_f32_16x16x32_bf16 v[80:83], v[182:185], v[206:209], v[80:83]
	v_mfma_f32_16x16x32_bf16 v[68:71], v[174:177], v[214:217], v[68:71]
	v_mfma_f32_16x16x32_bf16 v[64:67], v[182:185], v[214:217], v[64:67]
	s_barrier
	ds_read_b128 v[186:189], v155 offset:16384
	ds_read_b128 v[190:193], v155 offset:17408
	ds_read_b128 v[194:197], v155 offset:18432
	ds_read_b128 v[198:201], v155 offset:19456
	ds_read_b128 v[202:205], v155 offset:20480
	ds_read_b128 v[206:209], v155 offset:21504
	ds_read_b128 v[210:213], v155 offset:22528
	ds_read_b128 v[214:217], v155 offset:23552
	s_add_i32 s38, s54, s21
	v_lshl_add_u64 v[148:149], s[42:43], 0, v[132:133]
	s_mov_b32 m0, s38
	v_lshl_add_u64 v[218:219], s[42:43], 0, v[128:129]
	global_load_lds_dwordx4 v[148:149], off
	s_add_i32 m0, s38, 0x2000
	s_add_u32 s38, s42, 0x80000
	s_addc_u32 s39, s43, 0
	s_add_i32 s62, s55, s21
	global_load_lds_dwordx4 v[218:219], off
	v_lshl_add_u64 v[228:229], s[38:39], 0, v[132:133]
	s_mov_b32 m0, s62
	v_lshl_add_u64 v[220:221], s[44:45], 0, v[134:135]
	global_load_lds_dwordx4 v[228:229], off
	v_lshl_add_u64 v[228:229], s[38:39], 0, v[128:129]
	s_add_i32 m0, s62, 0x2000
	v_lshl_add_u64 v[222:223], s[44:45], 0, v[130:131]
	global_load_lds_dwordx4 v[228:229], off
	s_mov_b32 m0, s37
	s_nop 0
	global_load_lds_dwordx4 v[220:221], off
	s_mov_b32 m0, s47
	s_nop 0
	global_load_lds_dwordx4 v[222:223], off
	s_waitcnt vmcnt(8)
	s_waitcnt lgkmcnt(0)
	s_barrier
	s_waitcnt lgkmcnt(0)
	v_mfma_f32_16x16x32_bf16 v[60:63], v[144:147], v[186:189], v[60:63]
	v_mfma_f32_16x16x32_bf16 v[56:59], v[162:165], v[186:189], v[56:59]
	v_mfma_f32_16x16x32_bf16 v[44:47], v[144:147], v[194:197], v[44:47]
	v_mfma_f32_16x16x32_bf16 v[40:43], v[162:165], v[194:197], v[40:43]
	v_mfma_f32_16x16x32_bf16 v[28:31], v[144:147], v[202:205], v[28:31]
	v_mfma_f32_16x16x32_bf16 v[24:27], v[162:165], v[202:205], v[24:27]
	v_mfma_f32_16x16x32_bf16 v[12:15], v[144:147], v[210:213], v[12:15]
	v_mfma_f32_16x16x32_bf16 v[8:11], v[162:165], v[210:213], v[8:11]
	v_mfma_f32_16x16x32_bf16 v[60:63], v[158:161], v[190:193], v[60:63]
	v_mfma_f32_16x16x32_bf16 v[56:59], v[166:169], v[190:193], v[56:59]
	v_mfma_f32_16x16x32_bf16 v[44:47], v[158:161], v[198:201], v[44:47]
	v_mfma_f32_16x16x32_bf16 v[40:43], v[166:169], v[198:201], v[40:43]
	v_mfma_f32_16x16x32_bf16 v[28:31], v[158:161], v[206:209], v[28:31]
	v_mfma_f32_16x16x32_bf16 v[24:27], v[166:169], v[206:209], v[24:27]
	v_mfma_f32_16x16x32_bf16 v[12:15], v[158:161], v[214:217], v[12:15]
	v_mfma_f32_16x16x32_bf16 v[8:11], v[166:169], v[214:217], v[8:11]
	v_mfma_f32_16x16x32_bf16 v[52:55], v[170:173], v[186:189], v[52:55]
	v_mfma_f32_16x16x32_bf16 v[48:51], v[178:181], v[186:189], v[48:51]
	v_mfma_f32_16x16x32_bf16 v[36:39], v[170:173], v[194:197], v[36:39]
	v_mfma_f32_16x16x32_bf16 v[32:35], v[178:181], v[194:197], v[32:35]
	v_mfma_f32_16x16x32_bf16 v[20:23], v[170:173], v[202:205], v[20:23]
	v_mfma_f32_16x16x32_bf16 v[16:19], v[178:181], v[202:205], v[16:19]
	v_mfma_f32_16x16x32_bf16 v[4:7], v[170:173], v[210:213], v[4:7]
	v_mfma_f32_16x16x32_bf16 v[0:3], v[178:181], v[210:213], v[0:3]
	v_mfma_f32_16x16x32_bf16 v[52:55], v[174:177], v[190:193], v[52:55]
	v_mfma_f32_16x16x32_bf16 v[48:51], v[182:185], v[190:193], v[48:51]
	v_mfma_f32_16x16x32_bf16 v[36:39], v[174:177], v[198:201], v[36:39]
	v_mfma_f32_16x16x32_bf16 v[32:35], v[182:185], v[198:201], v[32:35]
	v_mfma_f32_16x16x32_bf16 v[20:23], v[174:177], v[206:209], v[20:23]
	v_mfma_f32_16x16x32_bf16 v[16:19], v[182:185], v[206:209], v[16:19]
	v_mfma_f32_16x16x32_bf16 v[4:7], v[174:177], v[214:217], v[4:7]
	v_mfma_f32_16x16x32_bf16 v[0:3], v[182:185], v[214:217], v[0:3]
	s_barrier
	s_add_i32 s62, 0, 0x18000
	v_add_u32_e32 v157, s62, v150
	s_add_i32 s63, 0, 0x1c000
	ds_read_b128 v[144:147], v157
	ds_read_b128 v[158:161], v157 offset:1024
	ds_read_b128 v[162:165], v157 offset:2048
	ds_read_b128 v[166:169], v157 offset:3072
	v_add_u32_e32 v157, s63, v150
	ds_read_b128 v[170:173], v157
	ds_read_b128 v[174:177], v157 offset:1024
	ds_read_b128 v[178:181], v157 offset:2048
	ds_read_b128 v[182:185], v157 offset:3072
	ds_read_b128 v[186:189], v155 offset:32768
	ds_read_b128 v[190:193], v155 offset:33792
	ds_read_b128 v[194:197], v155 offset:34816
	ds_read_b128 v[198:201], v155 offset:35840
	ds_read_b128 v[202:205], v155 offset:36864
	ds_read_b128 v[206:209], v155 offset:37888
	ds_read_b128 v[210:213], v155 offset:38912
	ds_read_b128 v[214:217], v155 offset:39936
	s_add_u32 s38, s44, 0x80000
	s_addc_u32 s39, s45, 0
	s_mov_b32 m0, s48
	v_lshl_add_u64 v[228:229], s[38:39], 0, v[134:135]
	global_load_lds_dwordx4 v[228:229], off
	v_lshl_add_u64 v[228:229], s[38:39], 0, v[130:131]
	s_mov_b32 m0, s49
	s_nop 0
	global_load_lds_dwordx4 v[228:229], off
	s_waitcnt vmcnt(8)
	s_waitcnt lgkmcnt(0)
	s_barrier
	s_waitcnt lgkmcnt(0)
	v_mfma_f32_16x16x32_bf16 v[124:127], v[144:147], v[186:189], v[124:127]
	v_mfma_f32_16x16x32_bf16 v[120:123], v[162:165], v[186:189], v[120:123]
	v_mfma_f32_16x16x32_bf16 v[108:111], v[144:147], v[194:197], v[108:111]
	v_mfma_f32_16x16x32_bf16 v[104:107], v[162:165], v[194:197], v[104:107]
	v_mfma_f32_16x16x32_bf16 v[92:95], v[144:147], v[202:205], v[92:95]
	v_mfma_f32_16x16x32_bf16 v[88:91], v[162:165], v[202:205], v[88:91]
	v_mfma_f32_16x16x32_bf16 v[76:79], v[144:147], v[210:213], v[76:79]
	v_mfma_f32_16x16x32_bf16 v[72:75], v[162:165], v[210:213], v[72:75]
	v_mfma_f32_16x16x32_bf16 v[124:127], v[158:161], v[190:193], v[124:127]
	v_mfma_f32_16x16x32_bf16 v[120:123], v[166:169], v[190:193], v[120:123]
	v_mfma_f32_16x16x32_bf16 v[108:111], v[158:161], v[198:201], v[108:111]
	v_mfma_f32_16x16x32_bf16 v[104:107], v[166:169], v[198:201], v[104:107]
	v_mfma_f32_16x16x32_bf16 v[92:95], v[158:161], v[206:209], v[92:95]
	v_mfma_f32_16x16x32_bf16 v[88:91], v[166:169], v[206:209], v[88:91]
	v_mfma_f32_16x16x32_bf16 v[76:79], v[158:161], v[214:217], v[76:79]
	v_mfma_f32_16x16x32_bf16 v[72:75], v[166:169], v[214:217], v[72:75]
	v_mfma_f32_16x16x32_bf16 v[116:119], v[170:173], v[186:189], v[116:119]
	v_mfma_f32_16x16x32_bf16 v[112:115], v[178:181], v[186:189], v[112:115]
	v_mfma_f32_16x16x32_bf16 v[100:103], v[170:173], v[194:197], v[100:103]
	v_mfma_f32_16x16x32_bf16 v[96:99], v[178:181], v[194:197], v[96:99]
	v_mfma_f32_16x16x32_bf16 v[84:87], v[170:173], v[202:205], v[84:87]
	v_mfma_f32_16x16x32_bf16 v[80:83], v[178:181], v[202:205], v[80:83]
	v_mfma_f32_16x16x32_bf16 v[68:71], v[170:173], v[210:213], v[68:71]
	v_mfma_f32_16x16x32_bf16 v[64:67], v[178:181], v[210:213], v[64:67]
	v_mfma_f32_16x16x32_bf16 v[116:119], v[174:177], v[190:193], v[116:119]
	v_mfma_f32_16x16x32_bf16 v[112:115], v[182:185], v[190:193], v[112:115]
	v_mfma_f32_16x16x32_bf16 v[100:103], v[174:177], v[198:201], v[100:103]
	v_mfma_f32_16x16x32_bf16 v[96:99], v[182:185], v[198:201], v[96:99]
	v_mfma_f32_16x16x32_bf16 v[84:87], v[174:177], v[206:209], v[84:87]
	v_mfma_f32_16x16x32_bf16 v[80:83], v[182:185], v[206:209], v[80:83]
	v_mfma_f32_16x16x32_bf16 v[68:71], v[174:177], v[214:217], v[68:71]
	v_mfma_f32_16x16x32_bf16 v[64:67], v[182:185], v[214:217], v[64:67]
	s_barrier
	ds_read_b128 v[186:189], v155 offset:49152
	ds_read_b128 v[190:193], v155 offset:50176
	ds_read_b128 v[194:197], v155 offset:51200
	ds_read_b128 v[198:201], v155 offset:52224
	ds_read_b128 v[202:205], v155 offset:53248
	ds_read_b128 v[206:209], v155 offset:54272
	ds_read_b128 v[210:213], v155 offset:55296
	ds_read_b128 v[214:217], v155 offset:56320
	s_add_i32 s38, s62, s21
	v_lshl_add_u64 v[148:149], v[148:149], 0, s[16:17]
	s_mov_b32 m0, s38
	s_nop 0
	global_load_lds_dwordx4 v[148:149], off
	s_add_i32 m0, s38, 0x2000
	s_add_u32 s38, s42, 0x80080
	v_lshl_add_u64 v[148:149], v[218:219], 0, s[16:17]
	s_addc_u32 s39, s43, 0
	s_add_i32 s42, s63, s21
	global_load_lds_dwordx4 v[148:149], off
	v_lshl_add_u64 v[148:149], s[38:39], 0, v[132:133]
	s_mov_b32 m0, s42
	s_nop 0
	global_load_lds_dwordx4 v[148:149], off
	v_lshl_add_u64 v[148:149], s[38:39], 0, v[128:129]
	s_add_i32 m0, s42, 0x2000
	s_nop 0
	global_load_lds_dwordx4 v[148:149], off
	v_lshl_add_u64 v[148:149], v[220:221], 0, s[16:17]
	s_mov_b32 m0, s51
	s_nop 0
	global_load_lds_dwordx4 v[148:149], off
	v_lshl_add_u64 v[148:149], v[222:223], 0, s[16:17]
	s_mov_b32 m0, s52
	s_nop 0
	global_load_lds_dwordx4 v[148:149], off
	s_waitcnt vmcnt(8)
	s_waitcnt lgkmcnt(0)
	s_barrier
	s_waitcnt lgkmcnt(0)
	v_mfma_f32_16x16x32_bf16 v[60:63], v[144:147], v[186:189], v[60:63]
	v_mfma_f32_16x16x32_bf16 v[56:59], v[162:165], v[186:189], v[56:59]
	v_mfma_f32_16x16x32_bf16 v[44:47], v[144:147], v[194:197], v[44:47]
	v_mfma_f32_16x16x32_bf16 v[40:43], v[162:165], v[194:197], v[40:43]
	v_mfma_f32_16x16x32_bf16 v[28:31], v[144:147], v[202:205], v[28:31]
	v_mfma_f32_16x16x32_bf16 v[24:27], v[162:165], v[202:205], v[24:27]
	v_mfma_f32_16x16x32_bf16 v[12:15], v[144:147], v[210:213], v[12:15]
	v_mfma_f32_16x16x32_bf16 v[8:11], v[162:165], v[210:213], v[8:11]
	v_mfma_f32_16x16x32_bf16 v[60:63], v[158:161], v[190:193], v[60:63]
	v_mfma_f32_16x16x32_bf16 v[56:59], v[166:169], v[190:193], v[56:59]
	v_mfma_f32_16x16x32_bf16 v[44:47], v[158:161], v[198:201], v[44:47]
	v_mfma_f32_16x16x32_bf16 v[40:43], v[166:169], v[198:201], v[40:43]
	v_mfma_f32_16x16x32_bf16 v[28:31], v[158:161], v[206:209], v[28:31]
	v_mfma_f32_16x16x32_bf16 v[24:27], v[166:169], v[206:209], v[24:27]
	v_mfma_f32_16x16x32_bf16 v[12:15], v[158:161], v[214:217], v[12:15]
	v_mfma_f32_16x16x32_bf16 v[8:11], v[166:169], v[214:217], v[8:11]
	v_mfma_f32_16x16x32_bf16 v[52:55], v[170:173], v[186:189], v[52:55]
	v_mfma_f32_16x16x32_bf16 v[48:51], v[178:181], v[186:189], v[48:51]
	v_mfma_f32_16x16x32_bf16 v[36:39], v[170:173], v[194:197], v[36:39]
	v_mfma_f32_16x16x32_bf16 v[32:35], v[178:181], v[194:197], v[32:35]
	v_mfma_f32_16x16x32_bf16 v[20:23], v[170:173], v[202:205], v[20:23]
	v_mfma_f32_16x16x32_bf16 v[16:19], v[178:181], v[202:205], v[16:19]
	v_mfma_f32_16x16x32_bf16 v[4:7], v[170:173], v[210:213], v[4:7]
	v_mfma_f32_16x16x32_bf16 v[0:3], v[178:181], v[210:213], v[0:3]
	v_mfma_f32_16x16x32_bf16 v[52:55], v[174:177], v[190:193], v[52:55]
	v_mfma_f32_16x16x32_bf16 v[48:51], v[182:185], v[190:193], v[48:51]
	v_mfma_f32_16x16x32_bf16 v[36:39], v[174:177], v[198:201], v[36:39]
	v_mfma_f32_16x16x32_bf16 v[32:35], v[182:185], v[198:201], v[32:35]
	v_mfma_f32_16x16x32_bf16 v[20:23], v[174:177], v[206:209], v[20:23]
	v_mfma_f32_16x16x32_bf16 v[16:19], v[182:185], v[206:209], v[16:19]
	v_mfma_f32_16x16x32_bf16 v[4:7], v[174:177], v[214:217], v[4:7]
	v_mfma_f32_16x16x32_bf16 v[0:3], v[182:185], v[214:217], v[0:3]
	s_barrier
	s_add_i32 s61, s61, 2
	s_add_u32 s59, s59, 0x100
	s_addc_u32 s60, s60, 0
	s_cmp_gt_u32 s61, 29
	s_mov_b64 s[38:39], s[40:41]
	s_cbranch_scc0 .LBB0_1240
	s_setprio 0
	s_and_b64 vcc, exec, s[6:7]
	s_cbranch_vccz .LBB0_1243
	s_barrier

.Lgprio5:
.LBB0_1327:
	ds_read_b128 v[144:147], v151
	ds_read_b128 v[154:157], v151 offset:1024
	ds_read_b128 v[158:161], v151 offset:2048
	ds_read_b128 v[162:165], v151 offset:3072
	ds_read_b128 v[166:169], v152
	ds_read_b128 v[170:173], v152 offset:1024
	ds_read_b128 v[174:177], v152 offset:2048
	ds_read_b128 v[178:181], v152 offset:3072
	ds_read_b128 v[182:185], v153
	ds_read_b128 v[186:189], v153 offset:1024
	ds_read_b128 v[190:193], v153 offset:2048
	ds_read_b128 v[194:197], v153 offset:3072
	ds_read_b128 v[198:201], v153 offset:4096
	ds_read_b128 v[202:205], v153 offset:5120
	ds_read_b128 v[206:209], v153 offset:6144
	ds_read_b128 v[210:213], v153 offset:7168
	s_add_u32 s34, s30, 0x100
	s_addc_u32 s35, s31, 0
	s_cmpk_eq_i32 s55, 0x54
	s_cselect_b32 s39, s5, s35
	s_cselect_b32 s38, s4, s34
	s_cselect_b32 s37, s29, s54
	s_cselect_b32 s36, s28, s53
	v_lshl_add_u64 v[228:229], s[30:31], 0, v[136:137]
	s_add_i32 m0, s40, 0xc000
	s_nop 0
	global_load_lds_dwordx4 v[228:229], off
	v_lshl_add_u64 v[228:229], s[30:31], 0, v[138:139]
	s_add_i32 m0, s40, 0xe000
	s_nop 0
	global_load_lds_dwordx4 v[228:229], off
	s_waitcnt vmcnt(8)
	s_waitcnt lgkmcnt(0)
	s_barrier
	s_waitcnt lgkmcnt(0)
	v_mfma_f32_16x16x32_bf16 v[124:127], v[144:147], v[182:185], v[124:127]
	v_mfma_f32_16x16x32_bf16 v[120:123], v[158:161], v[182:185], v[120:123]
	v_mfma_f32_16x16x32_bf16 v[108:111], v[144:147], v[190:193], v[108:111]
	v_mfma_f32_16x16x32_bf16 v[104:107], v[158:161], v[190:193], v[104:107]
	v_mfma_f32_16x16x32_bf16 v[92:95], v[144:147], v[198:201], v[92:95]
	v_mfma_f32_16x16x32_bf16 v[88:91], v[158:161], v[198:201], v[88:91]
	v_mfma_f32_16x16x32_bf16 v[76:79], v[144:147], v[206:209], v[76:79]
	v_mfma_f32_16x16x32_bf16 v[72:75], v[158:161], v[206:209], v[72:75]
	v_mfma_f32_16x16x32_bf16 v[124:127], v[154:157], v[186:189], v[124:127]
	v_mfma_f32_16x16x32_bf16 v[120:123], v[162:165], v[186:189], v[120:123]
	v_mfma_f32_16x16x32_bf16 v[108:111], v[154:157], v[194:197], v[108:111]
	v_mfma_f32_16x16x32_bf16 v[104:107], v[162:165], v[194:197], v[104:107]
	v_mfma_f32_16x16x32_bf16 v[92:95], v[154:157], v[202:205], v[92:95]
	v_mfma_f32_16x16x32_bf16 v[88:91], v[162:165], v[202:205], v[88:91]
	v_mfma_f32_16x16x32_bf16 v[76:79], v[154:157], v[210:213], v[76:79]
	v_mfma_f32_16x16x32_bf16 v[72:75], v[162:165], v[210:213], v[72:75]
	v_mfma_f32_16x16x32_bf16 v[116:119], v[166:169], v[182:185], v[116:119]
	v_mfma_f32_16x16x32_bf16 v[112:115], v[174:177], v[182:185], v[112:115]
	v_mfma_f32_16x16x32_bf16 v[100:103], v[166:169], v[190:193], v[100:103]
	v_mfma_f32_16x16x32_bf16 v[96:99], v[174:177], v[190:193], v[96:99]
	v_mfma_f32_16x16x32_bf16 v[84:87], v[166:169], v[198:201], v[84:87]
	v_mfma_f32_16x16x32_bf16 v[80:83], v[174:177], v[198:201], v[80:83]
	v_mfma_f32_16x16x32_bf16 v[68:71], v[166:169], v[206:209], v[68:71]
	v_mfma_f32_16x16x32_bf16 v[64:67], v[174:177], v[206:209], v[64:67]
	v_mfma_f32_16x16x32_bf16 v[116:119], v[170:173], v[186:189], v[116:119]
	v_mfma_f32_16x16x32_bf16 v[112:115], v[178:181], v[186:189], v[112:115]
	v_mfma_f32_16x16x32_bf16 v[100:103], v[170:173], v[194:197], v[100:103]
	v_mfma_f32_16x16x32_bf16 v[96:99], v[178:181], v[194:197], v[96:99]
	v_mfma_f32_16x16x32_bf16 v[84:87], v[170:173], v[202:205], v[84:87]
	v_mfma_f32_16x16x32_bf16 v[80:83], v[178:181], v[202:205], v[80:83]
	v_mfma_f32_16x16x32_bf16 v[68:71], v[170:173], v[210:213], v[68:71]
	v_mfma_f32_16x16x32_bf16 v[64:67], v[178:181], v[210:213], v[64:67]
	s_barrier
	ds_read_b128 v[182:185], v153 offset:16384
	ds_read_b128 v[186:189], v153 offset:17408
	ds_read_b128 v[190:193], v153 offset:18432
	ds_read_b128 v[194:197], v153 offset:19456
	ds_read_b128 v[198:201], v153 offset:20480
	ds_read_b128 v[202:205], v153 offset:21504
	ds_read_b128 v[206:209], v153 offset:22528
	ds_read_b128 v[210:213], v153 offset:23552
	s_add_i32 s30, s48, s23
	v_lshl_add_u64 v[214:215], s[36:37], 0, v[130:131]
	s_mov_b32 m0, s30
	v_lshl_add_u64 v[216:217], s[36:37], 0, v[134:135]
	global_load_lds_dwordx4 v[214:215], off
	s_add_i32 m0, s30, 0x2000
	s_add_u32 s30, s36, 0x160000
	s_addc_u32 s31, s37, 0
	s_add_i32 s56, s49, s23
	global_load_lds_dwordx4 v[216:217], off
	v_lshl_add_u64 v[228:229], s[30:31], 0, v[130:131]
	s_mov_b32 m0, s56
	v_lshl_add_u64 v[218:219], s[38:39], 0, v[128:129]
	global_load_lds_dwordx4 v[228:229], off
	v_lshl_add_u64 v[228:229], s[30:31], 0, v[134:135]
	s_add_i32 m0, s56, 0x2000
	v_lshl_add_u64 v[220:221], s[38:39], 0, v[132:133]
	global_load_lds_dwordx4 v[228:229], off
	s_mov_b32 m0, s40
	s_nop 0
	global_load_lds_dwordx4 v[218:219], off
	s_mov_b32 m0, s41
	s_nop 0
	global_load_lds_dwordx4 v[220:221], off
	s_waitcnt vmcnt(8)
	s_waitcnt lgkmcnt(0)
	s_barrier
	s_waitcnt lgkmcnt(0)
	v_mfma_f32_16x16x32_bf16 v[60:63], v[144:147], v[182:185], v[60:63]
	v_mfma_f32_16x16x32_bf16 v[56:59], v[158:161], v[182:185], v[56:59]
	v_mfma_f32_16x16x32_bf16 v[44:47], v[144:147], v[190:193], v[44:47]
	v_mfma_f32_16x16x32_bf16 v[40:43], v[158:161], v[190:193], v[40:43]
	v_mfma_f32_16x16x32_bf16 v[28:31], v[144:147], v[198:201], v[28:31]
	v_mfma_f32_16x16x32_bf16 v[24:27], v[158:161], v[198:201], v[24:27]
	v_mfma_f32_16x16x32_bf16 v[12:15], v[144:147], v[206:209], v[12:15]
	v_mfma_f32_16x16x32_bf16 v[8:11], v[158:161], v[206:209], v[8:11]
	v_mfma_f32_16x16x32_bf16 v[60:63], v[154:157], v[186:189], v[60:63]
	v_mfma_f32_16x16x32_bf16 v[56:59], v[162:165], v[186:189], v[56:59]
	v_mfma_f32_16x16x32_bf16 v[44:47], v[154:157], v[194:197], v[44:47]
	v_mfma_f32_16x16x32_bf16 v[40:43], v[162:165], v[194:197], v[40:43]
	v_mfma_f32_16x16x32_bf16 v[28:31], v[154:157], v[202:205], v[28:31]
	v_mfma_f32_16x16x32_bf16 v[24:27], v[162:165], v[202:205], v[24:27]
	v_mfma_f32_16x16x32_bf16 v[12:15], v[154:157], v[210:213], v[12:15]
	v_mfma_f32_16x16x32_bf16 v[8:11], v[162:165], v[210:213], v[8:11]
	v_mfma_f32_16x16x32_bf16 v[52:55], v[166:169], v[182:185], v[52:55]
	v_mfma_f32_16x16x32_bf16 v[48:51], v[174:177], v[182:185], v[48:51]
	v_mfma_f32_16x16x32_bf16 v[36:39], v[166:169], v[190:193], v[36:39]
	v_mfma_f32_16x16x32_bf16 v[32:35], v[174:177], v[190:193], v[32:35]
	v_mfma_f32_16x16x32_bf16 v[20:23], v[166:169], v[198:201], v[20:23]
	v_mfma_f32_16x16x32_bf16 v[16:19], v[174:177], v[198:201], v[16:19]
	v_mfma_f32_16x16x32_bf16 v[4:7], v[166:169], v[206:209], v[4:7]
	v_mfma_f32_16x16x32_bf16 v[0:3], v[174:177], v[206:209], v[0:3]
	v_mfma_f32_16x16x32_bf16 v[52:55], v[170:173], v[186:189], v[52:55]
	v_mfma_f32_16x16x32_bf16 v[48:51], v[178:181], v[186:189], v[48:51]
	v_mfma_f32_16x16x32_bf16 v[36:39], v[170:173], v[194:197], v[36:39]
	v_mfma_f32_16x16x32_bf16 v[32:35], v[178:181], v[194:197], v[32:35]
	v_mfma_f32_16x16x32_bf16 v[20:23], v[170:173], v[202:205], v[20:23]
	v_mfma_f32_16x16x32_bf16 v[16:19], v[178:181], v[202:205], v[16:19]
	v_mfma_f32_16x16x32_bf16 v[4:7], v[170:173], v[210:213], v[4:7]
	v_mfma_f32_16x16x32_bf16 v[0:3], v[178:181], v[210:213], v[0:3]
	s_barrier
	s_add_i32 s56, 0, 0x18000
	s_add_i32 s57, 0, 0x1c000
	v_add_u32_e32 v162, s56, v148
	v_add_u32_e32 v178, s57, v148
	ds_read_b128 v[144:147], v162
	ds_read_b128 v[154:157], v162 offset:1024
	ds_read_b128 v[158:161], v162 offset:2048
	ds_read_b128 v[162:165], v162 offset:3072
	ds_read_b128 v[166:169], v178
	ds_read_b128 v[170:173], v178 offset:1024
	ds_read_b128 v[174:177], v178 offset:2048
	ds_read_b128 v[178:181], v178 offset:3072
	ds_read_b128 v[182:185], v153 offset:32768
	ds_read_b128 v[186:189], v153 offset:33792
	ds_read_b128 v[190:193], v153 offset:34816
	ds_read_b128 v[194:197], v153 offset:35840
	ds_read_b128 v[198:201], v153 offset:36864
	ds_read_b128 v[202:205], v153 offset:37888
	ds_read_b128 v[206:209], v153 offset:38912
	ds_read_b128 v[210:213], v153 offset:39936
	s_add_u32 s30, s38, 0x160000
	s_addc_u32 s31, s39, 0
	s_mov_b32 m0, s42
	v_lshl_add_u64 v[228:229], s[30:31], 0, v[128:129]
	global_load_lds_dwordx4 v[228:229], off
	v_lshl_add_u64 v[228:229], s[30:31], 0, v[132:133]
	s_mov_b32 m0, s43
	s_nop 0
	global_load_lds_dwordx4 v[228:229], off
	s_waitcnt vmcnt(8)
	s_waitcnt lgkmcnt(0)
	s_barrier
	s_waitcnt lgkmcnt(0)
	v_mfma_f32_16x16x32_bf16 v[124:127], v[144:147], v[182:185], v[124:127]
	v_mfma_f32_16x16x32_bf16 v[120:123], v[158:161], v[182:185], v[120:123]
	v_mfma_f32_16x16x32_bf16 v[108:111], v[144:147], v[190:193], v[108:111]
	v_mfma_f32_16x16x32_bf16 v[104:107], v[158:161], v[190:193], v[104:107]
	v_mfma_f32_16x16x32_bf16 v[92:95], v[144:147], v[198:201], v[92:95]
	v_mfma_f32_16x16x32_bf16 v[88:91], v[158:161], v[198:201], v[88:91]
	v_mfma_f32_16x16x32_bf16 v[76:79], v[144:147], v[206:209], v[76:79]
	v_mfma_f32_16x16x32_bf16 v[72:75], v[158:161], v[206:209], v[72:75]
	v_mfma_f32_16x16x32_bf16 v[124:127], v[154:157], v[186:189], v[124:127]
	v_mfma_f32_16x16x32_bf16 v[120:123], v[162:165], v[186:189], v[120:123]
	v_mfma_f32_16x16x32_bf16 v[108:111], v[154:157], v[194:197], v[108:111]
	v_mfma_f32_16x16x32_bf16 v[104:107], v[162:165], v[194:197], v[104:107]
	v_mfma_f32_16x16x32_bf16 v[92:95], v[154:157], v[202:205], v[92:95]
	v_mfma_f32_16x16x32_bf16 v[88:91], v[162:165], v[202:205], v[88:91]
	v_mfma_f32_16x16x32_bf16 v[76:79], v[154:157], v[210:213], v[76:79]
	v_mfma_f32_16x16x32_bf16 v[72:75], v[162:165], v[210:213], v[72:75]
	v_mfma_f32_16x16x32_bf16 v[116:119], v[166:169], v[182:185], v[116:119]
	v_mfma_f32_16x16x32_bf16 v[112:115], v[174:177], v[182:185], v[112:115]
	v_mfma_f32_16x16x32_bf16 v[100:103], v[166:169], v[190:193], v[100:103]
	v_mfma_f32_16x16x32_bf16 v[96:99], v[174:177], v[190:193], v[96:99]
	v_mfma_f32_16x16x32_bf16 v[84:87], v[166:169], v[198:201], v[84:87]
	v_mfma_f32_16x16x32_bf16 v[80:83], v[174:177], v[198:201], v[80:83]
	v_mfma_f32_16x16x32_bf16 v[68:71], v[166:169], v[206:209], v[68:71]
	v_mfma_f32_16x16x32_bf16 v[64:67], v[174:177], v[206:209], v[64:67]
	v_mfma_f32_16x16x32_bf16 v[116:119], v[170:173], v[186:189], v[116:119]
	v_mfma_f32_16x16x32_bf16 v[112:115], v[178:181], v[186:189], v[112:115]
	v_mfma_f32_16x16x32_bf16 v[100:103], v[170:173], v[194:197], v[100:103]
	v_mfma_f32_16x16x32_bf16 v[96:99], v[178:181], v[194:197], v[96:99]
	v_mfma_f32_16x16x32_bf16 v[84:87], v[170:173], v[202:205], v[84:87]
	v_mfma_f32_16x16x32_bf16 v[80:83], v[178:181], v[202:205], v[80:83]
	v_mfma_f32_16x16x32_bf16 v[68:71], v[170:173], v[210:213], v[68:71]
	v_mfma_f32_16x16x32_bf16 v[64:67], v[178:181], v[210:213], v[64:67]
	s_barrier
	ds_read_b128 v[182:185], v153 offset:49152
	ds_read_b128 v[186:189], v153 offset:50176
	ds_read_b128 v[190:193], v153 offset:51200
	ds_read_b128 v[194:197], v153 offset:52224
	ds_read_b128 v[198:201], v153 offset:53248
	ds_read_b128 v[202:205], v153 offset:54272
	ds_read_b128 v[206:209], v153 offset:55296
	ds_read_b128 v[210:213], v153 offset:56320
	s_add_i32 s30, s56, s23
	v_lshl_add_u64 v[228:229], v[214:215], 0, s[16:17]
	s_mov_b32 m0, s30
	s_nop 0
	global_load_lds_dwordx4 v[228:229], off
	s_add_i32 m0, s30, 0x2000
	s_add_u32 s30, s36, 0x160080
	v_lshl_add_u64 v[228:229], v[216:217], 0, s[16:17]
	s_addc_u32 s31, s37, 0
	s_add_i32 s36, s57, s23
	global_load_lds_dwordx4 v[228:229], off
	v_lshl_add_u64 v[228:229], s[30:31], 0, v[130:131]
	s_mov_b32 m0, s36
	s_nop 0
	global_load_lds_dwordx4 v[228:229], off
	v_lshl_add_u64 v[228:229], s[30:31], 0, v[134:135]
	s_add_i32 m0, s36, 0x2000
	s_nop 0
	global_load_lds_dwordx4 v[228:229], off
	v_lshl_add_u64 v[228:229], v[218:219], 0, s[16:17]
	s_mov_b32 m0, s45
	s_nop 0
	global_load_lds_dwordx4 v[228:229], off
	v_lshl_add_u64 v[228:229], v[220:221], 0, s[16:17]
	s_mov_b32 m0, s46
	s_nop 0
	global_load_lds_dwordx4 v[228:229], off
	s_waitcnt vmcnt(8)
	s_waitcnt lgkmcnt(0)
	s_barrier
	s_waitcnt lgkmcnt(0)
	v_mfma_f32_16x16x32_bf16 v[60:63], v[144:147], v[182:185], v[60:63]
	v_mfma_f32_16x16x32_bf16 v[56:59], v[158:161], v[182:185], v[56:59]
	v_mfma_f32_16x16x32_bf16 v[44:47], v[144:147], v[190:193], v[44:47]
	v_mfma_f32_16x16x32_bf16 v[40:43], v[158:161], v[190:193], v[40:43]
	v_mfma_f32_16x16x32_bf16 v[28:31], v[144:147], v[198:201], v[28:31]
	v_mfma_f32_16x16x32_bf16 v[24:27], v[158:161], v[198:201], v[24:27]
	v_mfma_f32_16x16x32_bf16 v[12:15], v[144:147], v[206:209], v[12:15]
	v_mfma_f32_16x16x32_bf16 v[8:11], v[158:161], v[206:209], v[8:11]
	v_mfma_f32_16x16x32_bf16 v[60:63], v[154:157], v[186:189], v[60:63]
	v_mfma_f32_16x16x32_bf16 v[56:59], v[162:165], v[186:189], v[56:59]
	v_mfma_f32_16x16x32_bf16 v[44:47], v[154:157], v[194:197], v[44:47]
	v_mfma_f32_16x16x32_bf16 v[40:43], v[162:165], v[194:197], v[40:43]
	v_mfma_f32_16x16x32_bf16 v[28:31], v[154:157], v[202:205], v[28:31]
	v_mfma_f32_16x16x32_bf16 v[24:27], v[162:165], v[202:205], v[24:27]
	v_mfma_f32_16x16x32_bf16 v[12:15], v[154:157], v[210:213], v[12:15]
	v_mfma_f32_16x16x32_bf16 v[8:11], v[162:165], v[210:213], v[8:11]
	v_mfma_f32_16x16x32_bf16 v[52:55], v[166:169], v[182:185], v[52:55]
	v_mfma_f32_16x16x32_bf16 v[48:51], v[174:177], v[182:185], v[48:51]
	v_mfma_f32_16x16x32_bf16 v[36:39], v[166:169], v[190:193], v[36:39]
	v_mfma_f32_16x16x32_bf16 v[32:35], v[174:177], v[190:193], v[32:35]
	v_mfma_f32_16x16x32_bf16 v[20:23], v[166:169], v[198:201], v[20:23]
	v_mfma_f32_16x16x32_bf16 v[16:19], v[174:177], v[198:201], v[16:19]
	v_mfma_f32_16x16x32_bf16 v[4:7], v[166:169], v[206:209], v[4:7]
	v_mfma_f32_16x16x32_bf16 v[0:3], v[174:177], v[206:209], v[0:3]
	v_mfma_f32_16x16x32_bf16 v[52:55], v[170:173], v[186:189], v[52:55]
	v_mfma_f32_16x16x32_bf16 v[48:51], v[178:181], v[186:189], v[48:51]
	v_mfma_f32_16x16x32_bf16 v[36:39], v[170:173], v[194:197], v[36:39]
	v_mfma_f32_16x16x32_bf16 v[32:35], v[178:181], v[194:197], v[32:35]
	v_mfma_f32_16x16x32_bf16 v[20:23], v[170:173], v[202:205], v[20:23]
	v_mfma_f32_16x16x32_bf16 v[16:19], v[178:181], v[202:205], v[16:19]
	v_mfma_f32_16x16x32_bf16 v[4:7], v[170:173], v[210:213], v[4:7]
	v_mfma_f32_16x16x32_bf16 v[0:3], v[178:181], v[210:213], v[0:3]
	s_barrier
	s_add_i32 s55, s55, 2
	s_add_u32 s53, s53, 0x100
	s_addc_u32 s54, s54, 0
	s_cmpk_gt_u32 s55, 0x55
	s_mov_b64 s[30:31], s[34:35]
	s_cbranch_scc0 .LBB0_1327
	s_setprio 0
	s_and_b64 vcc, exec, s[8:9]
	s_cbranch_vccz .LBB0_1330
	s_barrier
